# prep RWKV finalize hand-written: rows/constants loaded up front per channel half, 8-token interleaved DPP reductions, stores never waited
# speedup vs baseline: 1.1034x; 1.0118x over previous
; template <bool RWONLY>
; __device__ __forceinline__ void phase_prep(const Params p, int l, char* smem) {
;     ...
;       for (int l4 = 0; l4 < 16; ++l4) {
;         float wv[4][4][2];
; #pragma unroll
;         for (int ll = 0; ll < 4; ++ll) {
; #pragma unroll
;           for (int ch = 0; ch < 2; ++ch) {
;             int c = tid + ch * 256;
;             int li = l4 * 4 + ll;
;             wv[0][ll][ch] = wup[(size_t)(0 * 64 + li) * 512 + c];
;             wv[1][ll][ch] = wup[(size_t)(1 * 64 + li) * 512 + c];
;             wv[2][ll][ch] = aup[(size_t)(0 * 64 + li) * 512 + c];
;             wv[3][ll][ch] = aup[(size_t)(1 * 64 + li) * 512 + c];
;           }
;         }
; #pragma unroll
;         for (int tk = 0; tk < 8; ++tk) {
; #pragma unroll
;           for (int mat = 0; mat < 4; ++mat) {
;             float4 d = *(const float4*)(ld + tk * 256 + mat * 64 + l4 * 4);
; #pragma unroll
;             for (int ch = 0; ch < 2; ++ch) {
;               acc[tk][mat][ch] += d.x * wv[mat][0][ch] + d.y * wv[mat][1][ch] + d.z * wv[mat][2][ch] + d.w * wv[mat][3][ch];
;             }
;           }
;         }
;       }
.Lprep_l4_join:
	v_mov_b32_e32 v172, s31
	s_add_i32 s31, s31, 16
	ds_read_b128 v[240:243], v172
	ds_read_b128 v[248:251], v172 offset:256
	ds_read_b128 v[252:255], v172 offset:512
	ds_read_b128 v[176:179], v172 offset:768
	s_waitcnt lgkmcnt(2)
	s_waitcnt vmcnt(32)
	v_pk_fma_f32 v[124:125], v[214:215], v[240:241], v[124:125] op_sel:[1,0,0] op_sel_hi:[0,0,1]
	v_pk_fma_f32 v[120:121], v[222:223], v[248:249], v[120:121] op_sel:[1,0,0] op_sel_hi:[0,0,1]
	v_pk_fma_f32 v[124:125], v[216:217], v[240:241], v[124:125] op_sel:[1,1,0] op_sel_hi:[0,1,1]
	v_pk_fma_f32 v[120:121], v[224:225], v[248:249], v[120:121] op_sel:[1,1,0] op_sel_hi:[0,1,1]
	v_pk_fma_f32 v[124:125], v[218:219], v[242:243], v[124:125] op_sel:[1,0,0] op_sel_hi:[0,0,1]
	v_pk_fma_f32 v[120:121], v[226:227], v[250:251], v[120:121] op_sel:[1,0,0] op_sel_hi:[0,0,1]
	v_pk_fma_f32 v[124:125], v[220:221], v[242:243], v[124:125] op_sel:[1,1,0] op_sel_hi:[0,1,1]
	v_pk_fma_f32 v[120:121], v[228:229], v[250:251], v[120:121] op_sel:[1,1,0] op_sel_hi:[0,1,1]
	ds_read_b128 v[240:243], v172 offset:1024
	ds_read_b128 v[248:251], v172 offset:1280
	s_waitcnt lgkmcnt(2)
	v_pk_fma_f32 v[122:123], v[230:231], v[252:253], v[122:123] op_sel:[1,0,0] op_sel_hi:[0,0,1]
	v_pk_fma_f32 v[118:119], v[182:183], v[176:177], v[118:119] op_sel:[1,0,0] op_sel_hi:[0,0,1]
	v_pk_fma_f32 v[122:123], v[232:233], v[252:253], v[122:123] op_sel:[1,1,0] op_sel_hi:[0,1,1]
	v_pk_fma_f32 v[118:119], v[184:185], v[176:177], v[118:119] op_sel:[1,1,0] op_sel_hi:[0,1,1]
	v_pk_fma_f32 v[122:123], v[234:235], v[254:255], v[122:123] op_sel:[1,0,0] op_sel_hi:[0,0,1]
	v_pk_fma_f32 v[118:119], v[186:187], v[178:179], v[118:119] op_sel:[1,0,0] op_sel_hi:[0,0,1]
	v_pk_fma_f32 v[122:123], v[180:181], v[254:255], v[122:123] op_sel:[1,1,0] op_sel_hi:[0,1,1]
	v_pk_fma_f32 v[118:119], v[188:189], v[178:179], v[118:119] op_sel:[1,1,0] op_sel_hi:[0,1,1]
	ds_read_b128 v[252:255], v172 offset:1536
	ds_read_b128 v[176:179], v172 offset:1792
	s_waitcnt lgkmcnt(2)
	v_pk_fma_f32 v[116:117], v[214:215], v[240:241], v[116:117] op_sel:[1,0,0] op_sel_hi:[0,0,1]
	v_pk_fma_f32 v[110:111], v[222:223], v[248:249], v[110:111] op_sel:[1,0,0] op_sel_hi:[0,0,1]
	v_pk_fma_f32 v[116:117], v[216:217], v[240:241], v[116:117] op_sel:[1,1,0] op_sel_hi:[0,1,1]
	v_pk_fma_f32 v[110:111], v[224:225], v[248:249], v[110:111] op_sel:[1,1,0] op_sel_hi:[0,1,1]
	v_pk_fma_f32 v[116:117], v[218:219], v[242:243], v[116:117] op_sel:[1,0,0] op_sel_hi:[0,0,1]
	v_pk_fma_f32 v[110:111], v[226:227], v[250:251], v[110:111] op_sel:[1,0,0] op_sel_hi:[0,0,1]
	v_pk_fma_f32 v[116:117], v[220:221], v[242:243], v[116:117] op_sel:[1,1,0] op_sel_hi:[0,1,1]
	v_pk_fma_f32 v[110:111], v[228:229], v[250:251], v[110:111] op_sel:[1,1,0] op_sel_hi:[0,1,1]
	ds_read_b128 v[240:243], v172 offset:2048
	ds_read_b128 v[248:251], v172 offset:2304
	s_waitcnt lgkmcnt(2)
	v_pk_fma_f32 v[114:115], v[230:231], v[252:253], v[114:115] op_sel:[1,0,0] op_sel_hi:[0,0,1]
	v_pk_fma_f32 v[112:113], v[182:183], v[176:177], v[112:113] op_sel:[1,0,0] op_sel_hi:[0,0,1]
	v_pk_fma_f32 v[114:115], v[232:233], v[252:253], v[114:115] op_sel:[1,1,0] op_sel_hi:[0,1,1]
	v_pk_fma_f32 v[112:113], v[184:185], v[176:177], v[112:113] op_sel:[1,1,0] op_sel_hi:[0,1,1]
	v_pk_fma_f32 v[114:115], v[234:235], v[254:255], v[114:115] op_sel:[1,0,0] op_sel_hi:[0,0,1]
	v_pk_fma_f32 v[112:113], v[186:187], v[178:179], v[112:113] op_sel:[1,0,0] op_sel_hi:[0,0,1]
	v_pk_fma_f32 v[114:115], v[180:181], v[254:255], v[114:115] op_sel:[1,1,0] op_sel_hi:[0,1,1]
	v_pk_fma_f32 v[112:113], v[188:189], v[178:179], v[112:113] op_sel:[1,1,0] op_sel_hi:[0,1,1]
	ds_read_b128 v[252:255], v172 offset:2560
	ds_read_b128 v[176:179], v172 offset:2816
	s_waitcnt lgkmcnt(2)
	v_pk_fma_f32 v[108:109], v[214:215], v[240:241], v[108:109] op_sel:[1,0,0] op_sel_hi:[0,0,1]
	v_pk_fma_f32 v[102:103], v[222:223], v[248:249], v[102:103] op_sel:[1,0,0] op_sel_hi:[0,0,1]
	v_pk_fma_f32 v[108:109], v[216:217], v[240:241], v[108:109] op_sel:[1,1,0] op_sel_hi:[0,1,1]
	v_pk_fma_f32 v[102:103], v[224:225], v[248:249], v[102:103] op_sel:[1,1,0] op_sel_hi:[0,1,1]
	v_pk_fma_f32 v[108:109], v[218:219], v[242:243], v[108:109] op_sel:[1,0,0] op_sel_hi:[0,0,1]
	v_pk_fma_f32 v[102:103], v[226:227], v[250:251], v[102:103] op_sel:[1,0,0] op_sel_hi:[0,0,1]
	v_pk_fma_f32 v[108:109], v[220:221], v[242:243], v[108:109] op_sel:[1,1,0] op_sel_hi:[0,1,1]
	v_pk_fma_f32 v[102:103], v[228:229], v[250:251], v[102:103] op_sel:[1,1,0] op_sel_hi:[0,1,1]
	ds_read_b128 v[240:243], v172 offset:3072
	ds_read_b128 v[248:251], v172 offset:3328
	s_waitcnt lgkmcnt(2)
	v_pk_fma_f32 v[106:107], v[230:231], v[252:253], v[106:107] op_sel:[1,0,0] op_sel_hi:[0,0,1]
	v_pk_fma_f32 v[104:105], v[182:183], v[176:177], v[104:105] op_sel:[1,0,0] op_sel_hi:[0,0,1]
	v_pk_fma_f32 v[106:107], v[232:233], v[252:253], v[106:107] op_sel:[1,1,0] op_sel_hi:[0,1,1]
	v_pk_fma_f32 v[104:105], v[184:185], v[176:177], v[104:105] op_sel:[1,1,0] op_sel_hi:[0,1,1]
	v_pk_fma_f32 v[106:107], v[234:235], v[254:255], v[106:107] op_sel:[1,0,0] op_sel_hi:[0,0,1]
	v_pk_fma_f32 v[104:105], v[186:187], v[178:179], v[104:105] op_sel:[1,0,0] op_sel_hi:[0,0,1]
	v_pk_fma_f32 v[106:107], v[180:181], v[254:255], v[106:107] op_sel:[1,1,0] op_sel_hi:[0,1,1]
	v_pk_fma_f32 v[104:105], v[188:189], v[178:179], v[104:105] op_sel:[1,1,0] op_sel_hi:[0,1,1]
	ds_read_b128 v[252:255], v172 offset:3584
	ds_read_b128 v[176:179], v172 offset:3840
	s_waitcnt lgkmcnt(2)
; template <bool RWONLY>
; __device__ __forceinline__ void phase_prep(const Params p, int l, char* smem) {
;     ...
;       for (int l4 = 0; l4 < 16; ++l4) {
;         float wv[4][4][2];
; #pragma unroll
;         for (int ll = 0; ll < 4; ++ll) {
; #pragma unroll
;           for (int ch = 0; ch < 2; ++ch) {
;             int c = tid + ch * 256;
;             int li = l4 * 4 + ll;
;             wv[0][ll][ch] = wup[(size_t)(0 * 64 + li) * 512 + c];
;             wv[1][ll][ch] = wup[(size_t)(1 * 64 + li) * 512 + c];
;             wv[2][ll][ch] = aup[(size_t)(0 * 64 + li) * 512 + c];
;             wv[3][ll][ch] = aup[(size_t)(1 * 64 + li) * 512 + c];
;           }
;         }
; #pragma unroll
;         for (int tk = 0; tk < 8; ++tk) {
; #pragma unroll
;           for (int mat = 0; mat < 4; ++mat) {
;             float4 d = *(const float4*)(ld + tk * 256 + mat * 64 + l4 * 4);
; #pragma unroll
;             for (int ch = 0; ch < 2; ++ch) {
;               acc[tk][mat][ch] += d.x * wv[mat][0][ch] + d.y * wv[mat][1][ch] + d.z * wv[mat][2][ch] + d.w * wv[mat][3][ch];
;             }
;           }
;         }
;       }
	v_pk_fma_f32 v[100:101], v[214:215], v[240:241], v[100:101] op_sel:[1,0,0] op_sel_hi:[0,0,1]
	v_pk_fma_f32 v[96:97], v[222:223], v[248:249], v[96:97] op_sel:[1,0,0] op_sel_hi:[0,0,1]
	v_pk_fma_f32 v[100:101], v[216:217], v[240:241], v[100:101] op_sel:[1,1,0] op_sel_hi:[0,1,1]
	v_pk_fma_f32 v[96:97], v[224:225], v[248:249], v[96:97] op_sel:[1,1,0] op_sel_hi:[0,1,1]
	v_pk_fma_f32 v[100:101], v[218:219], v[242:243], v[100:101] op_sel:[1,0,0] op_sel_hi:[0,0,1]
	v_pk_fma_f32 v[96:97], v[226:227], v[250:251], v[96:97] op_sel:[1,0,0] op_sel_hi:[0,0,1]
	v_pk_fma_f32 v[100:101], v[220:221], v[242:243], v[100:101] op_sel:[1,1,0] op_sel_hi:[0,1,1]
	v_pk_fma_f32 v[96:97], v[228:229], v[250:251], v[96:97] op_sel:[1,1,0] op_sel_hi:[0,1,1]
	ds_read_b128 v[240:243], v172 offset:4096
	ds_read_b128 v[248:251], v172 offset:4352
	s_waitcnt lgkmcnt(2)
	v_pk_fma_f32 v[98:99], v[230:231], v[252:253], v[98:99] op_sel:[1,0,0] op_sel_hi:[0,0,1]
	v_pk_fma_f32 v[94:95], v[182:183], v[176:177], v[94:95] op_sel:[1,0,0] op_sel_hi:[0,0,1]
	v_pk_fma_f32 v[98:99], v[232:233], v[252:253], v[98:99] op_sel:[1,1,0] op_sel_hi:[0,1,1]
	v_pk_fma_f32 v[94:95], v[184:185], v[176:177], v[94:95] op_sel:[1,1,0] op_sel_hi:[0,1,1]
	v_pk_fma_f32 v[98:99], v[234:235], v[254:255], v[98:99] op_sel:[1,0,0] op_sel_hi:[0,0,1]
	v_pk_fma_f32 v[94:95], v[186:187], v[178:179], v[94:95] op_sel:[1,0,0] op_sel_hi:[0,0,1]
	v_pk_fma_f32 v[98:99], v[180:181], v[254:255], v[98:99] op_sel:[1,1,0] op_sel_hi:[0,1,1]
	v_pk_fma_f32 v[94:95], v[188:189], v[178:179], v[94:95] op_sel:[1,1,0] op_sel_hi:[0,1,1]
	ds_read_b128 v[252:255], v172 offset:4608
	ds_read_b128 v[176:179], v172 offset:4864
	s_waitcnt lgkmcnt(2)
	v_pk_fma_f32 v[90:91], v[214:215], v[240:241], v[90:91] op_sel:[0,0,0] op_sel_hi:[1,0,1]
	v_pk_fma_f32 v[86:87], v[222:223], v[248:249], v[86:87] op_sel:[0,0,0] op_sel_hi:[1,0,1]
	v_pk_fma_f32 v[90:91], v[216:217], v[240:241], v[90:91] op_sel:[0,1,0] op_sel_hi:[1,1,1]
	v_pk_fma_f32 v[86:87], v[224:225], v[248:249], v[86:87] op_sel:[0,1,0] op_sel_hi:[1,1,1]
	v_pk_fma_f32 v[90:91], v[218:219], v[242:243], v[90:91] op_sel:[0,0,0] op_sel_hi:[1,0,1]
	v_pk_fma_f32 v[86:87], v[226:227], v[250:251], v[86:87] op_sel:[0,0,0] op_sel_hi:[1,0,1]
	v_pk_fma_f32 v[90:91], v[220:221], v[242:243], v[90:91] op_sel:[0,1,0] op_sel_hi:[1,1,1]
	v_pk_fma_f32 v[86:87], v[228:229], v[250:251], v[86:87] op_sel:[0,1,0] op_sel_hi:[1,1,1]
	ds_read_b128 v[240:243], v172 offset:5120
	ds_read_b128 v[248:251], v172 offset:5376
	s_waitcnt lgkmcnt(2)
	v_pk_fma_f32 v[92:93], v[230:231], v[252:253], v[92:93] op_sel:[0,0,0] op_sel_hi:[1,0,1]
	v_pk_fma_f32 v[88:89], v[182:183], v[176:177], v[88:89] op_sel:[0,0,0] op_sel_hi:[1,0,1]
	v_pk_fma_f32 v[92:93], v[232:233], v[252:253], v[92:93] op_sel:[0,1,0] op_sel_hi:[1,1,1]
	v_pk_fma_f32 v[88:89], v[184:185], v[176:177], v[88:89] op_sel:[0,1,0] op_sel_hi:[1,1,1]
	v_pk_fma_f32 v[92:93], v[234:235], v[254:255], v[92:93] op_sel:[0,0,0] op_sel_hi:[1,0,1]
	v_pk_fma_f32 v[88:89], v[186:187], v[178:179], v[88:89] op_sel:[0,0,0] op_sel_hi:[1,0,1]
	v_pk_fma_f32 v[92:93], v[180:181], v[254:255], v[92:93] op_sel:[0,1,0] op_sel_hi:[1,1,1]
	v_pk_fma_f32 v[88:89], v[188:189], v[178:179], v[88:89] op_sel:[0,1,0] op_sel_hi:[1,1,1]
	ds_read_b128 v[252:255], v172 offset:5632
	ds_read_b128 v[176:179], v172 offset:5888
	s_waitcnt lgkmcnt(2)
	v_pk_fma_f32 v[82:83], v[214:215], v[240:241], v[82:83] op_sel:[0,0,0] op_sel_hi:[1,0,1]
	v_pk_fma_f32 v[78:79], v[222:223], v[248:249], v[78:79] op_sel:[0,0,0] op_sel_hi:[1,0,1]
	v_pk_fma_f32 v[82:83], v[216:217], v[240:241], v[82:83] op_sel:[0,1,0] op_sel_hi:[1,1,1]
	v_pk_fma_f32 v[78:79], v[224:225], v[248:249], v[78:79] op_sel:[0,1,0] op_sel_hi:[1,1,1]
	v_pk_fma_f32 v[82:83], v[218:219], v[242:243], v[82:83] op_sel:[0,0,0] op_sel_hi:[1,0,1]
	v_pk_fma_f32 v[78:79], v[226:227], v[250:251], v[78:79] op_sel:[0,0,0] op_sel_hi:[1,0,1]
	v_pk_fma_f32 v[82:83], v[220:221], v[242:243], v[82:83] op_sel:[0,1,0] op_sel_hi:[1,1,1]
	v_pk_fma_f32 v[78:79], v[228:229], v[250:251], v[78:79] op_sel:[0,1,0] op_sel_hi:[1,1,1]
	ds_read_b128 v[240:243], v172 offset:6144
	ds_read_b128 v[248:251], v172 offset:6400
	s_waitcnt lgkmcnt(2)
	v_pk_fma_f32 v[84:85], v[230:231], v[252:253], v[84:85] op_sel:[0,0,0] op_sel_hi:[1,0,1]
	v_pk_fma_f32 v[80:81], v[182:183], v[176:177], v[80:81] op_sel:[0,0,0] op_sel_hi:[1,0,1]
	v_pk_fma_f32 v[84:85], v[232:233], v[252:253], v[84:85] op_sel:[0,1,0] op_sel_hi:[1,1,1]
	v_pk_fma_f32 v[80:81], v[184:185], v[176:177], v[80:81] op_sel:[0,1,0] op_sel_hi:[1,1,1]
	v_pk_fma_f32 v[84:85], v[234:235], v[254:255], v[84:85] op_sel:[0,0,0] op_sel_hi:[1,0,1]
	v_pk_fma_f32 v[80:81], v[186:187], v[178:179], v[80:81] op_sel:[0,0,0] op_sel_hi:[1,0,1]
	v_pk_fma_f32 v[84:85], v[180:181], v[254:255], v[84:85] op_sel:[0,1,0] op_sel_hi:[1,1,1]
	v_pk_fma_f32 v[80:81], v[188:189], v[178:179], v[80:81] op_sel:[0,1,0] op_sel_hi:[1,1,1]
	ds_read_b128 v[252:255], v172 offset:6656
	ds_read_b128 v[176:179], v172 offset:6912
	s_waitcnt lgkmcnt(2)
	v_pk_fma_f32 v[74:75], v[214:215], v[240:241], v[74:75] op_sel:[0,0,0] op_sel_hi:[1,0,1]
	v_pk_fma_f32 v[70:71], v[222:223], v[248:249], v[70:71] op_sel:[0,0,0] op_sel_hi:[1,0,1]
	v_pk_fma_f32 v[74:75], v[216:217], v[240:241], v[74:75] op_sel:[0,1,0] op_sel_hi:[1,1,1]
	v_pk_fma_f32 v[70:71], v[224:225], v[248:249], v[70:71] op_sel:[0,1,0] op_sel_hi:[1,1,1]
	v_pk_fma_f32 v[74:75], v[218:219], v[242:243], v[74:75] op_sel:[0,0,0] op_sel_hi:[1,0,1]
	v_pk_fma_f32 v[70:71], v[226:227], v[250:251], v[70:71] op_sel:[0,0,0] op_sel_hi:[1,0,1]
	v_pk_fma_f32 v[74:75], v[220:221], v[242:243], v[74:75] op_sel:[0,1,0] op_sel_hi:[1,1,1]
	v_pk_fma_f32 v[70:71], v[228:229], v[250:251], v[70:71] op_sel:[0,1,0] op_sel_hi:[1,1,1]
	ds_read_b128 v[240:243], v172 offset:7168
	ds_read_b128 v[248:251], v172 offset:7424
	s_waitcnt lgkmcnt(2)
; template <bool RWONLY>
; __device__ __forceinline__ void phase_prep(const Params p, int l, char* smem) {
;     ...
;       for (int l4 = 0; l4 < 16; ++l4) {
;         float wv[4][4][2];
; #pragma unroll
;         for (int ll = 0; ll < 4; ++ll) {
; #pragma unroll
;           for (int ch = 0; ch < 2; ++ch) {
;             int c = tid + ch * 256;
;             int li = l4 * 4 + ll;
;             wv[0][ll][ch] = wup[(size_t)(0 * 64 + li) * 512 + c];
;             wv[1][ll][ch] = wup[(size_t)(1 * 64 + li) * 512 + c];
;             wv[2][ll][ch] = aup[(size_t)(0 * 64 + li) * 512 + c];
;             wv[3][ll][ch] = aup[(size_t)(1 * 64 + li) * 512 + c];
;           }
;         }
; #pragma unroll
;         for (int tk = 0; tk < 8; ++tk) {
; #pragma unroll
;           for (int mat = 0; mat < 4; ++mat) {
;             float4 d = *(const float4*)(ld + tk * 256 + mat * 64 + l4 * 4);
; #pragma unroll
;             for (int ch = 0; ch < 2; ++ch) {
;               acc[tk][mat][ch] += d.x * wv[mat][0][ch] + d.y * wv[mat][1][ch] + d.z * wv[mat][2][ch] + d.w * wv[mat][3][ch];
;             }
;           }
;         }
;       }
;     ...
;       for (int ch = 0; ch < 2; ++ch) {
;         const int c = tid + ch * 256;
;         float shc[3][3];
; #pragma unroll
;         for (int q = 0; q < 3; ++q)
; #pragma unroll
;           for (int j = 0; j < 3; ++j) shc[q][j] = sh[j * 1792 + q * 512 + c];
;         const float kkc = kkp[c], kac = kap[c], rkc = rkp[c];
;         const float w0c0 = w0[c], w0c1 = w0[512 + c], a0c0 = a0[c], a0c1 = a0[512 + c];
;         float um[3], u0[3];
; #pragma unroll
;         for (int q = 0; q < 3; ++q) {
;           um[q] = s0 > 0 ? RWU[(size_t)(s0 - 1) * 1792 + q * 512 + c] : 0.f;
;           u0[q] = RWU[(size_t)s0 * 1792 + q * 512 + c];
;         }
	v_pk_fma_f32 v[76:77], v[230:231], v[252:253], v[76:77] op_sel:[0,0,0] op_sel_hi:[1,0,1]
	v_pk_fma_f32 v[72:73], v[182:183], v[176:177], v[72:73] op_sel:[0,0,0] op_sel_hi:[1,0,1]
	v_pk_fma_f32 v[76:77], v[232:233], v[252:253], v[76:77] op_sel:[0,1,0] op_sel_hi:[1,1,1]
	v_pk_fma_f32 v[72:73], v[184:185], v[176:177], v[72:73] op_sel:[0,1,0] op_sel_hi:[1,1,1]
	v_pk_fma_f32 v[76:77], v[234:235], v[254:255], v[76:77] op_sel:[0,0,0] op_sel_hi:[1,0,1]
	v_pk_fma_f32 v[72:73], v[186:187], v[178:179], v[72:73] op_sel:[0,0,0] op_sel_hi:[1,0,1]
	v_pk_fma_f32 v[76:77], v[180:181], v[254:255], v[76:77] op_sel:[0,1,0] op_sel_hi:[1,1,1]
	v_pk_fma_f32 v[72:73], v[188:189], v[178:179], v[72:73] op_sel:[0,1,0] op_sel_hi:[1,1,1]
	ds_read_b128 v[252:255], v172 offset:7680
	ds_read_b128 v[176:179], v172 offset:7936
	s_waitcnt lgkmcnt(2)
	v_pk_fma_f32 v[66:67], v[214:215], v[240:241], v[66:67] op_sel:[0,0,0] op_sel_hi:[1,0,1]
	v_pk_fma_f32 v[62:63], v[222:223], v[248:249], v[62:63] op_sel:[0,0,0] op_sel_hi:[1,0,1]
	v_pk_fma_f32 v[66:67], v[216:217], v[240:241], v[66:67] op_sel:[0,1,0] op_sel_hi:[1,1,1]
	v_pk_fma_f32 v[62:63], v[224:225], v[248:249], v[62:63] op_sel:[0,1,0] op_sel_hi:[1,1,1]
	v_pk_fma_f32 v[66:67], v[218:219], v[242:243], v[66:67] op_sel:[0,0,0] op_sel_hi:[1,0,1]
	v_pk_fma_f32 v[62:63], v[226:227], v[250:251], v[62:63] op_sel:[0,0,0] op_sel_hi:[1,0,1]
	v_pk_fma_f32 v[66:67], v[220:221], v[242:243], v[66:67] op_sel:[0,1,0] op_sel_hi:[1,1,1]
	v_pk_fma_f32 v[62:63], v[228:229], v[250:251], v[62:63] op_sel:[0,1,0] op_sel_hi:[1,1,1]
	s_waitcnt lgkmcnt(0)
	v_pk_fma_f32 v[68:69], v[230:231], v[252:253], v[68:69] op_sel:[0,0,0] op_sel_hi:[1,0,1]
	v_pk_fma_f32 v[64:65], v[182:183], v[176:177], v[64:65] op_sel:[0,0,0] op_sel_hi:[1,0,1]
	v_pk_fma_f32 v[68:69], v[232:233], v[252:253], v[68:69] op_sel:[0,1,0] op_sel_hi:[1,1,1]
	v_pk_fma_f32 v[64:65], v[184:185], v[176:177], v[64:65] op_sel:[0,1,0] op_sel_hi:[1,1,1]
	v_pk_fma_f32 v[68:69], v[234:235], v[254:255], v[68:69] op_sel:[0,0,0] op_sel_hi:[1,0,1]
	v_pk_fma_f32 v[64:65], v[186:187], v[178:179], v[64:65] op_sel:[0,0,0] op_sel_hi:[1,0,1]
	v_pk_fma_f32 v[68:69], v[180:181], v[254:255], v[68:69] op_sel:[0,1,0] op_sel_hi:[1,1,1]
	v_pk_fma_f32 v[64:65], v[188:189], v[178:179], v[64:65] op_sel:[0,1,0] op_sel_hi:[1,1,1]
	s_cmp_eq_u32 s90, 0x20000
	s_cbranch_scc0 .LBB0_365
	v_lshlrev_b32_e32 v126, 2, v160
	s_cmp_eq_u32 s56, 0
	s_cselect_b32 s24, 0, 1.0
	s_add_i32 s20, s56, 8
	s_cmpk_gt_u32 s20, 0x1fff
	s_cselect_b32 s25, 0, 1.0
	global_load_dword v130, v[2:3], off offset:0
	global_load_dword v131, v[14:15], off offset:0
	global_load_dword v132, v[16:17], off offset:0
	global_load_dword v133, v[2:3], off offset:2048
	global_load_dword v134, v[18:19], off offset:0
	global_load_dword v135, v[20:21], off offset:0
	global_load_dword v136, v[22:23], off offset:0
	global_load_dword v137, v[24:25], off offset:0
	global_load_dword v138, v[26:27], off offset:0
	global_load_dword v139, v[28:29], off
	global_load_dword v140, v[30:31], off
	global_load_dword v141, v[32:33], off
	global_load_dword v142, v[34:35], off
	global_load_dword v143, v[34:35], off offset:2048
	global_load_dword v144, v[36:37], off
	global_load_dword v145, v[36:37], off offset:2048
	s_add_i32 s20, s56, -1
	s_max_i32 s20, s20, 0
	s_mul_i32 s21, s20, 0x1c00
	s_add_u32 s21, s21, 0x24c40000
	v_add_u32_e32 v127, s21, v161
	v_add_u32_e32 v128, 0x1000, v127
	global_load_dword v146, v127, s[96:97]
	global_load_dword v147, v127, s[96:97] offset:2048
	global_load_dword v148, v128, s[96:97]
	s_add_i32 s20, s56, 0
	s_mul_i32 s21, s20, 0x1c00
	s_add_u32 s21, s21, 0x24c40000
	v_add_u32_e32 v127, s21, v161
	v_add_u32_e32 v128, 0x1000, v127
	global_load_dword v149, v127, s[96:97]
	global_load_dword v150, v127, s[96:97] offset:2048
	global_load_dword v151, v128, s[96:97]
	s_add_i32 s20, s56, 1
	s_mul_i32 s21, s20, 0x1c00
	s_add_u32 s21, s21, 0x24c40000
	v_add_u32_e32 v127, s21, v161
	v_add_u32_e32 v128, 0x1000, v127
	global_load_dword v152, v127, s[96:97]
	global_load_dword v153, v127, s[96:97] offset:2048
	global_load_dword v154, v128, s[96:97]
	s_add_i32 s20, s56, 2
	s_mul_i32 s21, s20, 0x1c00
	s_add_u32 s21, s21, 0x24c40000
	v_add_u32_e32 v127, s21, v161
	v_add_u32_e32 v128, 0x1000, v127
	global_load_dword v155, v127, s[96:97]
	global_load_dword v156, v127, s[96:97] offset:2048
	global_load_dword v157, v128, s[96:97]
	s_add_i32 s20, s56, 3
	s_mul_i32 s21, s20, 0x1c00
	s_add_u32 s21, s21, 0x24c40000
	v_add_u32_e32 v127, s21, v161
	v_add_u32_e32 v128, 0x1000, v127
	global_load_dword v158, v127, s[96:97]
	global_load_dword v159, v127, s[96:97] offset:2048
	global_load_dword v172, v128, s[96:97]
	s_add_i32 s20, s56, 4
	s_mul_i32 s21, s20, 0x1c00
	s_add_u32 s21, s21, 0x24c40000
	v_add_u32_e32 v127, s21, v161
	v_add_u32_e32 v128, 0x1000, v127
	global_load_dword v173, v127, s[96:97]
	global_load_dword v174, v127, s[96:97] offset:2048
	global_load_dword v175, v128, s[96:97]
	s_add_i32 s20, s56, 5
	s_mul_i32 s21, s20, 0x1c00
	s_add_u32 s21, s21, 0x24c40000
	v_add_u32_e32 v127, s21, v161
	v_add_u32_e32 v128, 0x1000, v127
	global_load_dword v176, v127, s[96:97]
	global_load_dword v177, v127, s[96:97] offset:2048
	global_load_dword v178, v128, s[96:97]
	s_add_i32 s20, s56, 6
	s_mul_i32 s21, s20, 0x1c00
	s_add_u32 s21, s21, 0x24c40000
	v_add_u32_e32 v127, s21, v161
	v_add_u32_e32 v128, 0x1000, v127
	global_load_dword v179, v127, s[96:97]
	global_load_dword v180, v127, s[96:97] offset:2048
	global_load_dword v181, v128, s[96:97]
	s_add_i32 s20, s56, 7
	s_mul_i32 s21, s20, 0x1c00
	s_add_u32 s21, s21, 0x24c40000
	v_add_u32_e32 v127, s21, v161
	v_add_u32_e32 v128, 0x1000, v127
	global_load_dword v182, v127, s[96:97]
	global_load_dword v183, v127, s[96:97] offset:2048
	global_load_dword v184, v128, s[96:97]
	s_add_i32 s20, s56, 8
	s_min_i32 s20, s20, 0x1fff
	s_mul_i32 s21, s20, 0x1c00
	s_add_u32 s21, s21, 0x24c40000
	v_add_u32_e32 v127, s21, v161
	v_add_u32_e32 v128, 0x1000, v127
	global_load_dword v185, v127, s[96:97]
	global_load_dword v186, v127, s[96:97] offset:2048
	global_load_dword v187, v128, s[96:97]
	s_waitcnt vmcnt(0)
; template <bool RWONLY>
; __device__ __forceinline__ void phase_prep(const Params p, int l, char* smem) {
;     ...
;       for (int ch = 0; ch < 2; ++ch) {
;         const int c = tid + ch * 256;
;         float shc[3][3];
; #pragma unroll
;         for (int q = 0; q < 3; ++q)
; #pragma unroll
;           for (int j = 0; j < 3; ++j) shc[q][j] = sh[j * 1792 + q * 512 + c];
;         const float kkc = kkp[c], kac = kap[c], rkc = rkp[c];
;         const float w0c0 = w0[c], w0c1 = w0[512 + c], a0c0 = a0[c], a0c1 = a0[512 + c];
;         float um[3], u0[3];
; #pragma unroll
;         for (int q = 0; q < 3; ++q) {
;           um[q] = s0 > 0 ? RWU[(size_t)(s0 - 1) * 1792 + q * 512 + c] : 0.f;
;           u0[q] = RWU[(size_t)s0 * 1792 + q * 512 + c];
;         }
; #pragma unroll
;         for (int tk = 0; tk < 8; ++tk) {
;           const int s = s0 + tk;
;           float rkv[3];
; #pragma unroll
;           for (int q = 0; q < 3; ++q) {
;             float up = s < S_ - 1 ? RWU[(size_t)(s + 1) * 1792 + q * 512 + c] : 0.f;
;             rkv[q] = shc[q][0] * um[q] + shc[q][1] * u0[q] + shc[q][2] * up;
;             um[q] = u0[q];
;             u0[q] = up;
;           }
;           float r = rkv[0], k = rkv[1], v = rkv[2];
;           float kkr = k * kkc;
;           float ss = wave_sum(kkr * kkr);
;           float kk = kkr * __builtin_amdgcn_rcpf(fmaxf(__builtin_amdgcn_sqrtf(ss), 1e-12f));
	v_mul_f32_e32 v146, s24, v146
	v_mul_f32_e32 v185, s25, v185
	v_mul_f32_e32 v147, s24, v147
	v_mul_f32_e32 v186, s25, v186
	v_mul_f32_e32 v148, s24, v148
	v_mul_f32_e32 v187, s25, v187
	v_mul_f32_e32 v188, v130, v146
	v_mul_f32_e32 v218, v133, v147
	v_mul_f32_e32 v226, v136, v148
	v_fmac_f32_e32 v188, v131, v149
	v_fmac_f32_e32 v218, v134, v150
	v_fmac_f32_e32 v226, v137, v151
	v_fmac_f32_e32 v188, v132, v152
	v_fmac_f32_e32 v218, v135, v153
	v_fmac_f32_e32 v226, v138, v154
	v_mul_f32_e32 v189, v130, v149
	v_mul_f32_e32 v219, v133, v150
	v_mul_f32_e32 v227, v136, v151
	v_fmac_f32_e32 v189, v131, v152
	v_fmac_f32_e32 v219, v134, v153
	v_fmac_f32_e32 v227, v137, v154
	v_fmac_f32_e32 v189, v132, v155
	v_fmac_f32_e32 v219, v135, v156
	v_fmac_f32_e32 v227, v138, v157
	v_mul_f32_e32 v190, v130, v152
	v_mul_f32_e32 v220, v133, v153
	v_mul_f32_e32 v228, v136, v154
	v_fmac_f32_e32 v190, v131, v155
	v_fmac_f32_e32 v220, v134, v156
	v_fmac_f32_e32 v228, v137, v157
	v_fmac_f32_e32 v190, v132, v158
	v_fmac_f32_e32 v220, v135, v159
	v_fmac_f32_e32 v228, v138, v172
	v_mul_f32_e32 v191, v130, v155
	v_mul_f32_e32 v221, v133, v156
	v_mul_f32_e32 v229, v136, v157
	v_fmac_f32_e32 v191, v131, v158
	v_fmac_f32_e32 v221, v134, v159
	v_fmac_f32_e32 v229, v137, v172
	v_fmac_f32_e32 v191, v132, v173
	v_fmac_f32_e32 v221, v135, v174
	v_fmac_f32_e32 v229, v138, v175
	v_mul_f32_e32 v214, v130, v158
	v_mul_f32_e32 v222, v133, v159
	v_mul_f32_e32 v230, v136, v172
	v_fmac_f32_e32 v214, v131, v173
	v_fmac_f32_e32 v222, v134, v174
	v_fmac_f32_e32 v230, v137, v175
	v_fmac_f32_e32 v214, v132, v176
	v_fmac_f32_e32 v222, v135, v177
	v_fmac_f32_e32 v230, v138, v178
	v_mul_f32_e32 v215, v130, v173
	v_mul_f32_e32 v223, v133, v174
	v_mul_f32_e32 v231, v136, v175
	v_fmac_f32_e32 v215, v131, v176
	v_fmac_f32_e32 v223, v134, v177
	v_fmac_f32_e32 v231, v137, v178
	v_fmac_f32_e32 v215, v132, v179
	v_fmac_f32_e32 v223, v135, v180
	v_fmac_f32_e32 v231, v138, v181
	v_mul_f32_e32 v216, v130, v176
	v_mul_f32_e32 v224, v133, v177
	v_mul_f32_e32 v232, v136, v178
	v_fmac_f32_e32 v216, v131, v179
	v_fmac_f32_e32 v224, v134, v180
	v_fmac_f32_e32 v232, v137, v181
	v_fmac_f32_e32 v216, v132, v182
	v_fmac_f32_e32 v224, v135, v183
	v_fmac_f32_e32 v232, v138, v184
	v_mul_f32_e32 v217, v130, v179
	v_mul_f32_e32 v225, v133, v180
	v_mul_f32_e32 v233, v136, v181
	v_fmac_f32_e32 v217, v131, v182
	v_fmac_f32_e32 v225, v134, v183
	v_fmac_f32_e32 v233, v137, v184
	v_fmac_f32_e32 v217, v132, v185
	v_fmac_f32_e32 v225, v135, v186
	v_fmac_f32_e32 v233, v138, v187
	v_mul_f32_e32 v146, v218, v139
	v_mul_f32_e32 v147, v219, v139
	v_mul_f32_e32 v148, v220, v139
	v_mul_f32_e32 v149, v221, v139
	v_mul_f32_e32 v150, v222, v139
	v_mul_f32_e32 v151, v223, v139
	v_mul_f32_e32 v152, v224, v139
	v_mul_f32_e32 v153, v225, v139
	v_mul_f32_e32 v154, v146, v146
	v_mul_f32_e32 v155, v147, v147
	v_mul_f32_e32 v156, v148, v148
	v_mul_f32_e32 v157, v149, v149
	v_mul_f32_e32 v158, v150, v150
	v_mul_f32_e32 v159, v151, v151
	v_mul_f32_e32 v172, v152, v152
	v_mul_f32_e32 v173, v153, v153
	v_add_f32_dpp v154, v154, v154 quad_perm:[1,0,3,2] row_mask:0xf bank_mask:0xf bound_ctrl:1
	v_add_f32_dpp v155, v155, v155 quad_perm:[1,0,3,2] row_mask:0xf bank_mask:0xf bound_ctrl:1
	v_add_f32_dpp v156, v156, v156 quad_perm:[1,0,3,2] row_mask:0xf bank_mask:0xf bound_ctrl:1
	v_add_f32_dpp v157, v157, v157 quad_perm:[1,0,3,2] row_mask:0xf bank_mask:0xf bound_ctrl:1
	v_add_f32_dpp v158, v158, v158 quad_perm:[1,0,3,2] row_mask:0xf bank_mask:0xf bound_ctrl:1
	v_add_f32_dpp v159, v159, v159 quad_perm:[1,0,3,2] row_mask:0xf bank_mask:0xf bound_ctrl:1
	v_add_f32_dpp v172, v172, v172 quad_perm:[1,0,3,2] row_mask:0xf bank_mask:0xf bound_ctrl:1
	v_add_f32_dpp v173, v173, v173 quad_perm:[1,0,3,2] row_mask:0xf bank_mask:0xf bound_ctrl:1
	v_add_f32_dpp v154, v154, v154 quad_perm:[2,3,0,1] row_mask:0xf bank_mask:0xf bound_ctrl:1
	v_add_f32_dpp v155, v155, v155 quad_perm:[2,3,0,1] row_mask:0xf bank_mask:0xf bound_ctrl:1
	v_add_f32_dpp v156, v156, v156 quad_perm:[2,3,0,1] row_mask:0xf bank_mask:0xf bound_ctrl:1
	v_add_f32_dpp v157, v157, v157 quad_perm:[2,3,0,1] row_mask:0xf bank_mask:0xf bound_ctrl:1
	v_add_f32_dpp v158, v158, v158 quad_perm:[2,3,0,1] row_mask:0xf bank_mask:0xf bound_ctrl:1
	v_add_f32_dpp v159, v159, v159 quad_perm:[2,3,0,1] row_mask:0xf bank_mask:0xf bound_ctrl:1
	v_add_f32_dpp v172, v172, v172 quad_perm:[2,3,0,1] row_mask:0xf bank_mask:0xf bound_ctrl:1
	v_add_f32_dpp v173, v173, v173 quad_perm:[2,3,0,1] row_mask:0xf bank_mask:0xf bound_ctrl:1
	v_add_f32_dpp v154, v154, v154 row_half_mirror row_mask:0xf bank_mask:0xf bound_ctrl:1
	v_add_f32_dpp v155, v155, v155 row_half_mirror row_mask:0xf bank_mask:0xf bound_ctrl:1
	v_add_f32_dpp v156, v156, v156 row_half_mirror row_mask:0xf bank_mask:0xf bound_ctrl:1
	v_add_f32_dpp v157, v157, v157 row_half_mirror row_mask:0xf bank_mask:0xf bound_ctrl:1
	v_add_f32_dpp v158, v158, v158 row_half_mirror row_mask:0xf bank_mask:0xf bound_ctrl:1
	v_add_f32_dpp v159, v159, v159 row_half_mirror row_mask:0xf bank_mask:0xf bound_ctrl:1
	v_add_f32_dpp v172, v172, v172 row_half_mirror row_mask:0xf bank_mask:0xf bound_ctrl:1
	v_add_f32_dpp v173, v173, v173 row_half_mirror row_mask:0xf bank_mask:0xf bound_ctrl:1
	v_add_f32_dpp v154, v154, v154 row_mirror row_mask:0xf bank_mask:0xf bound_ctrl:1
	v_add_f32_dpp v155, v155, v155 row_mirror row_mask:0xf bank_mask:0xf bound_ctrl:1
	v_add_f32_dpp v156, v156, v156 row_mirror row_mask:0xf bank_mask:0xf bound_ctrl:1
	v_add_f32_dpp v157, v157, v157 row_mirror row_mask:0xf bank_mask:0xf bound_ctrl:1
	v_add_f32_dpp v158, v158, v158 row_mirror row_mask:0xf bank_mask:0xf bound_ctrl:1
	v_add_f32_dpp v159, v159, v159 row_mirror row_mask:0xf bank_mask:0xf bound_ctrl:1
	v_add_f32_dpp v172, v172, v172 row_mirror row_mask:0xf bank_mask:0xf bound_ctrl:1
	v_add_f32_dpp v173, v173, v173 row_mirror row_mask:0xf bank_mask:0xf bound_ctrl:1
	ds_bpermute_b32 v174, v163, v154
	ds_bpermute_b32 v175, v163, v155
	ds_bpermute_b32 v176, v163, v156
	ds_bpermute_b32 v177, v163, v157
	ds_bpermute_b32 v178, v163, v158
	ds_bpermute_b32 v179, v163, v159
	ds_bpermute_b32 v180, v163, v172
	ds_bpermute_b32 v181, v163, v173
	s_waitcnt lgkmcnt(0)
; template <bool RWONLY>
; __device__ __forceinline__ void phase_prep(const Params p, int l, char* smem) {
;     ...
;           float r = rkv[0], k = rkv[1], v = rkv[2];
;           float kkr = k * kkc;
;           float ss = wave_sum(kkr * kkr);
;           float kk = kkr * __builtin_amdgcn_rcpf(fmaxf(__builtin_amdgcn_sqrtf(ss), 1e-12f));
;           float bsum = 0.f;
; #pragma unroll
;           for (int n = 0; n < 2; ++n) {
;             float zw = (n ? w0c1 : w0c0) + acc[tk][n][ch];
;             float za = (n ? a0c1 : a0c0) + acc[tk][2 + n][ch];
;             float dec = __expf(-0.6065306597126334f * sigmoidf_(zw));
;             float a = sigmoidf_(za);
;             float kd = k * (1.f + (a - 1.f) * kac);
;             float bb = kk * a;
;             size_t o = ((size_t)n * S_ + s) * 512 + c;
;             ((float*)(ws + OFF_SCW))[o] = dec;
;             ((float*)(ws + OFF_SCKD))[o] = kd;
;             ((float*)(ws + OFF_SCB))[o] = bb;
;             bsum += r * kd * rkc;
;           }
;           size_t o1 = (size_t)s * 512 + c;
;           ((float*)(ws + OFF_SCR))[o1] = r;
;           ((float*)(ws + OFF_SCV))[o1] = v;
;           ((float*)(ws + OFF_SCKK))[o1] = kk;
	v_add_f32_e32 v154, v154, v174
	v_add_f32_e32 v155, v155, v175
	v_add_f32_e32 v156, v156, v176
	v_add_f32_e32 v157, v157, v177
	v_add_f32_e32 v158, v158, v178
	v_add_f32_e32 v159, v159, v179
	v_add_f32_e32 v172, v172, v180
	v_add_f32_e32 v173, v173, v181
	ds_bpermute_b32 v174, v162, v154
	ds_bpermute_b32 v175, v162, v155
	ds_bpermute_b32 v176, v162, v156
	ds_bpermute_b32 v177, v162, v157
	ds_bpermute_b32 v178, v162, v158
	ds_bpermute_b32 v179, v162, v159
	ds_bpermute_b32 v180, v162, v172
	ds_bpermute_b32 v181, v162, v173
	s_waitcnt lgkmcnt(0)
	v_add_f32_e32 v154, v154, v174
	v_add_f32_e32 v155, v155, v175
	v_add_f32_e32 v156, v156, v176
	v_add_f32_e32 v157, v157, v177
	v_add_f32_e32 v158, v158, v178
	v_add_f32_e32 v159, v159, v179
	v_add_f32_e32 v172, v172, v180
	v_add_f32_e32 v173, v173, v181
	v_sqrt_f32_e32 v154, v154
	v_sqrt_f32_e32 v155, v155
	v_sqrt_f32_e32 v156, v156
	v_sqrt_f32_e32 v157, v157
	v_sqrt_f32_e32 v158, v158
	v_sqrt_f32_e32 v159, v159
	v_sqrt_f32_e32 v172, v172
	v_sqrt_f32_e32 v173, v173
	v_max_f32_e32 v154, 0x2b8cbccc, v154
	v_max_f32_e32 v155, 0x2b8cbccc, v155
	v_max_f32_e32 v156, 0x2b8cbccc, v156
	v_max_f32_e32 v157, 0x2b8cbccc, v157
	v_max_f32_e32 v158, 0x2b8cbccc, v158
	v_max_f32_e32 v159, 0x2b8cbccc, v159
	v_max_f32_e32 v172, 0x2b8cbccc, v172
	v_max_f32_e32 v173, 0x2b8cbccc, v173
	v_rcp_f32_e32 v154, v154
	v_rcp_f32_e32 v155, v155
	v_rcp_f32_e32 v156, v156
	v_rcp_f32_e32 v157, v157
	v_rcp_f32_e32 v158, v158
	v_rcp_f32_e32 v159, v159
	v_rcp_f32_e32 v172, v172
	v_rcp_f32_e32 v173, v173
	s_nop 0
	v_mul_f32_e32 v146, v146, v154
	v_mul_f32_e32 v147, v147, v155
	v_mul_f32_e32 v148, v148, v156
	v_mul_f32_e32 v149, v149, v157
	v_mul_f32_e32 v150, v150, v158
	v_mul_f32_e32 v151, v151, v159
	v_mul_f32_e32 v152, v152, v172
	v_mul_f32_e32 v153, v153, v173
	v_add_f32_e32 v174, v142, v125
	v_add_f32_e32 v176, v144, v123
	v_add_f32_e32 v175, v143, v121
	v_add_f32_e32 v177, v145, v119
	v_mul_f32_e32 v174, 0xbfb8aa3b, v174
	v_mul_f32_e32 v175, 0xbfb8aa3b, v175
	v_mul_f32_e32 v176, 0xbfb8aa3b, v176
	v_mul_f32_e32 v177, 0xbfb8aa3b, v177
	v_exp_f32_e32 v174, v174
	v_exp_f32_e32 v175, v175
	v_exp_f32_e32 v176, v176
	v_exp_f32_e32 v177, v177
	s_nop 0
	v_add_f32_e32 v174, 1.0, v174
	v_add_f32_e32 v175, 1.0, v175
	v_add_f32_e32 v176, 1.0, v176
	v_add_f32_e32 v177, 1.0, v177
	v_rcp_f32_e32 v174, v174
	v_rcp_f32_e32 v175, v175
	v_rcp_f32_e32 v176, v176
	v_rcp_f32_e32 v177, v177
	s_nop 0
	v_mul_f32_e32 v174, 0xbf1b4598, v174
	v_mul_f32_e32 v175, 0xbf1b4598, v175
	v_mul_f32_e32 v174, 0x3fb8aa3b, v174
	v_mul_f32_e32 v175, 0x3fb8aa3b, v175
	v_exp_f32_e32 v174, v174
	v_exp_f32_e32 v175, v175
	v_add_f32_e32 v178, -1.0, v176
	v_add_f32_e32 v179, -1.0, v177
	v_fma_f32 v178, v140, v178, 1.0
	v_fma_f32 v179, v140, v179, 1.0
	v_mul_f32_e32 v178, v178, v218
	v_mul_f32_e32 v180, v146, v176
	v_mul_f32_e32 v179, v179, v218
	v_mul_f32_e32 v181, v146, v177
	s_lshl_b32 s21, s56, 11
	s_add_u32 s21, s21, 0x2b440000
	v_add_u32_e32 v129, s21, v161
	global_store_dword v129, v174, s[96:97]
	s_lshl_b32 s21, s56, 11
	s_add_u32 s21, s21, 0x2d440000
	v_add_u32_e32 v129, s21, v161
	global_store_dword v129, v178, s[96:97]
	s_lshl_b32 s21, s56, 11
	s_add_u32 s21, s21, 0x2f440000
	v_add_u32_e32 v129, s21, v161
	global_store_dword v129, v180, s[96:97]
	s_lshl_b32 s21, s56, 11
	s_add_u32 s21, s21, 0x2c440000
	v_add_u32_e32 v129, s21, v161
	global_store_dword v129, v175, s[96:97]
	s_lshl_b32 s21, s56, 11
	s_add_u32 s21, s21, 0x2e440000
	v_add_u32_e32 v129, s21, v161
	global_store_dword v129, v179, s[96:97]
	s_lshl_b32 s21, s56, 11
	s_add_u32 s21, s21, 0x30440000
	v_add_u32_e32 v129, s21, v161
	global_store_dword v129, v181, s[96:97]
	v_mul_f32_e32 v182, v188, v178
	v_mul_f32_e32 v183, v188, v179
	v_mul_f32_e32 v154, v141, v182
	v_fmac_f32_e32 v154, v141, v183
	s_lshl_b32 s21, s56, 11
	s_add_u32 s21, s21, 0x28440000
	v_add_u32_e32 v129, s21, v161
	global_store_dword v129, v188, s[96:97]
	s_lshl_b32 s21, s56, 11
	s_add_u32 s21, s21, 0x29440000
	v_add_u32_e32 v129, s21, v161
	global_store_dword v129, v226, s[96:97]
	s_lshl_b32 s21, s56, 11
	s_add_u32 s21, s21, 0x2a440000
	v_add_u32_e32 v129, s21, v161
	global_store_dword v129, v146, s[96:97]
	v_add_f32_e32 v174, v142, v117
	v_add_f32_e32 v176, v144, v115
	v_add_f32_e32 v175, v143, v111
	v_add_f32_e32 v177, v145, v113
	v_mul_f32_e32 v174, 0xbfb8aa3b, v174
	v_mul_f32_e32 v175, 0xbfb8aa3b, v175
	v_mul_f32_e32 v176, 0xbfb8aa3b, v176
	v_mul_f32_e32 v177, 0xbfb8aa3b, v177
	v_exp_f32_e32 v174, v174
	v_exp_f32_e32 v175, v175
	v_exp_f32_e32 v176, v176
	v_exp_f32_e32 v177, v177
	s_nop 0
	v_add_f32_e32 v174, 1.0, v174
	v_add_f32_e32 v175, 1.0, v175
	v_add_f32_e32 v176, 1.0, v176
	v_add_f32_e32 v177, 1.0, v177
	v_rcp_f32_e32 v174, v174
	v_rcp_f32_e32 v175, v175
	v_rcp_f32_e32 v176, v176
	v_rcp_f32_e32 v177, v177
	s_nop 0
	v_mul_f32_e32 v174, 0xbf1b4598, v174
	v_mul_f32_e32 v175, 0xbf1b4598, v175
	v_mul_f32_e32 v174, 0x3fb8aa3b, v174
	v_mul_f32_e32 v175, 0x3fb8aa3b, v175
	v_exp_f32_e32 v174, v174
	v_exp_f32_e32 v175, v175
	v_add_f32_e32 v178, -1.0, v176
	v_add_f32_e32 v179, -1.0, v177
	v_fma_f32 v178, v140, v178, 1.0
	v_fma_f32 v179, v140, v179, 1.0
	v_mul_f32_e32 v178, v178, v219
	v_mul_f32_e32 v180, v147, v176
	v_mul_f32_e32 v179, v179, v219
	v_mul_f32_e32 v181, v147, v177
	s_lshl_b32 s21, s56, 11
	s_add_u32 s21, s21, 0x2b440800
	v_add_u32_e32 v129, s21, v161
	global_store_dword v129, v174, s[96:97]
	s_lshl_b32 s21, s56, 11
	s_add_u32 s21, s21, 0x2d440800
	v_add_u32_e32 v129, s21, v161
	global_store_dword v129, v178, s[96:97]
	s_lshl_b32 s21, s56, 11
	s_add_u32 s21, s21, 0x2f440800
	v_add_u32_e32 v129, s21, v161
	global_store_dword v129, v180, s[96:97]
; template <bool RWONLY>
; __device__ __forceinline__ void phase_prep(const Params p, int l, char* smem) {
;     ...
;           float bsum = 0.f;
; #pragma unroll
;           for (int n = 0; n < 2; ++n) {
;             float zw = (n ? w0c1 : w0c0) + acc[tk][n][ch];
;             float za = (n ? a0c1 : a0c0) + acc[tk][2 + n][ch];
;             float dec = __expf(-0.6065306597126334f * sigmoidf_(zw));
;             float a = sigmoidf_(za);
;             float kd = k * (1.f + (a - 1.f) * kac);
;             float bb = kk * a;
;             size_t o = ((size_t)n * S_ + s) * 512 + c;
;             ((float*)(ws + OFF_SCW))[o] = dec;
;             ((float*)(ws + OFF_SCKD))[o] = kd;
;             ((float*)(ws + OFF_SCB))[o] = bb;
;             bsum += r * kd * rkc;
;           }
;           size_t o1 = (size_t)s * 512 + c;
;           ((float*)(ws + OFF_SCR))[o1] = r;
;           ((float*)(ws + OFF_SCV))[o1] = v;
;           ((float*)(ws + OFF_SCKK))[o1] = kk;
	s_lshl_b32 s21, s56, 11
	s_add_u32 s21, s21, 0x2c440800
	v_add_u32_e32 v129, s21, v161
	global_store_dword v129, v175, s[96:97]
	s_lshl_b32 s21, s56, 11
	s_add_u32 s21, s21, 0x2e440800
	v_add_u32_e32 v129, s21, v161
	global_store_dword v129, v179, s[96:97]
	s_lshl_b32 s21, s56, 11
	s_add_u32 s21, s21, 0x30440800
	v_add_u32_e32 v129, s21, v161
	global_store_dword v129, v181, s[96:97]
	v_mul_f32_e32 v182, v189, v178
	v_mul_f32_e32 v183, v189, v179
	v_mul_f32_e32 v155, v141, v182
	v_fmac_f32_e32 v155, v141, v183
	s_lshl_b32 s21, s56, 11
	s_add_u32 s21, s21, 0x28440800
	v_add_u32_e32 v129, s21, v161
	global_store_dword v129, v189, s[96:97]
	s_lshl_b32 s21, s56, 11
	s_add_u32 s21, s21, 0x29440800
	v_add_u32_e32 v129, s21, v161
	global_store_dword v129, v227, s[96:97]
	s_lshl_b32 s21, s56, 11
	s_add_u32 s21, s21, 0x2a440800
	v_add_u32_e32 v129, s21, v161
	global_store_dword v129, v147, s[96:97]
	v_add_f32_e32 v174, v142, v109
	v_add_f32_e32 v176, v144, v107
	v_add_f32_e32 v175, v143, v103
	v_add_f32_e32 v177, v145, v105
	v_mul_f32_e32 v174, 0xbfb8aa3b, v174
	v_mul_f32_e32 v175, 0xbfb8aa3b, v175
	v_mul_f32_e32 v176, 0xbfb8aa3b, v176
	v_mul_f32_e32 v177, 0xbfb8aa3b, v177
	v_exp_f32_e32 v174, v174
	v_exp_f32_e32 v175, v175
	v_exp_f32_e32 v176, v176
	v_exp_f32_e32 v177, v177
	s_nop 0
	v_add_f32_e32 v174, 1.0, v174
	v_add_f32_e32 v175, 1.0, v175
	v_add_f32_e32 v176, 1.0, v176
	v_add_f32_e32 v177, 1.0, v177
	v_rcp_f32_e32 v174, v174
	v_rcp_f32_e32 v175, v175
	v_rcp_f32_e32 v176, v176
	v_rcp_f32_e32 v177, v177
	s_nop 0
	v_mul_f32_e32 v174, 0xbf1b4598, v174
	v_mul_f32_e32 v175, 0xbf1b4598, v175
	v_mul_f32_e32 v174, 0x3fb8aa3b, v174
	v_mul_f32_e32 v175, 0x3fb8aa3b, v175
	v_exp_f32_e32 v174, v174
	v_exp_f32_e32 v175, v175
	v_add_f32_e32 v178, -1.0, v176
	v_add_f32_e32 v179, -1.0, v177
	v_fma_f32 v178, v140, v178, 1.0
	v_fma_f32 v179, v140, v179, 1.0
	v_mul_f32_e32 v178, v178, v220
	v_mul_f32_e32 v180, v148, v176
	v_mul_f32_e32 v179, v179, v220
	v_mul_f32_e32 v181, v148, v177
	s_lshl_b32 s21, s56, 11
	s_add_u32 s21, s21, 0x2b441000
	v_add_u32_e32 v129, s21, v161
	global_store_dword v129, v174, s[96:97]
	s_lshl_b32 s21, s56, 11
	s_add_u32 s21, s21, 0x2d441000
	v_add_u32_e32 v129, s21, v161
	global_store_dword v129, v178, s[96:97]
	s_lshl_b32 s21, s56, 11
	s_add_u32 s21, s21, 0x2f441000
	v_add_u32_e32 v129, s21, v161
	global_store_dword v129, v180, s[96:97]
	s_lshl_b32 s21, s56, 11
	s_add_u32 s21, s21, 0x2c441000
	v_add_u32_e32 v129, s21, v161
	global_store_dword v129, v175, s[96:97]
	s_lshl_b32 s21, s56, 11
	s_add_u32 s21, s21, 0x2e441000
	v_add_u32_e32 v129, s21, v161
	global_store_dword v129, v179, s[96:97]
	s_lshl_b32 s21, s56, 11
	s_add_u32 s21, s21, 0x30441000
	v_add_u32_e32 v129, s21, v161
	global_store_dword v129, v181, s[96:97]
	v_mul_f32_e32 v182, v190, v178
	v_mul_f32_e32 v183, v190, v179
	v_mul_f32_e32 v156, v141, v182
	v_fmac_f32_e32 v156, v141, v183
	s_lshl_b32 s21, s56, 11
	s_add_u32 s21, s21, 0x28441000
	v_add_u32_e32 v129, s21, v161
	global_store_dword v129, v190, s[96:97]
	s_lshl_b32 s21, s56, 11
	s_add_u32 s21, s21, 0x29441000
	v_add_u32_e32 v129, s21, v161
	global_store_dword v129, v228, s[96:97]
	s_lshl_b32 s21, s56, 11
	s_add_u32 s21, s21, 0x2a441000
	v_add_u32_e32 v129, s21, v161
	global_store_dword v129, v148, s[96:97]
	v_add_f32_e32 v174, v142, v101
	v_add_f32_e32 v176, v144, v99
	v_add_f32_e32 v175, v143, v97
	v_add_f32_e32 v177, v145, v95
	v_mul_f32_e32 v174, 0xbfb8aa3b, v174
	v_mul_f32_e32 v175, 0xbfb8aa3b, v175
	v_mul_f32_e32 v176, 0xbfb8aa3b, v176
	v_mul_f32_e32 v177, 0xbfb8aa3b, v177
	v_exp_f32_e32 v174, v174
	v_exp_f32_e32 v175, v175
	v_exp_f32_e32 v176, v176
	v_exp_f32_e32 v177, v177
	s_nop 0
	v_add_f32_e32 v174, 1.0, v174
	v_add_f32_e32 v175, 1.0, v175
	v_add_f32_e32 v176, 1.0, v176
	v_add_f32_e32 v177, 1.0, v177
	v_rcp_f32_e32 v174, v174
	v_rcp_f32_e32 v175, v175
	v_rcp_f32_e32 v176, v176
	v_rcp_f32_e32 v177, v177
	s_nop 0
	v_mul_f32_e32 v174, 0xbf1b4598, v174
	v_mul_f32_e32 v175, 0xbf1b4598, v175
	v_mul_f32_e32 v174, 0x3fb8aa3b, v174
	v_mul_f32_e32 v175, 0x3fb8aa3b, v175
	v_exp_f32_e32 v174, v174
	v_exp_f32_e32 v175, v175
	v_add_f32_e32 v178, -1.0, v176
	v_add_f32_e32 v179, -1.0, v177
	v_fma_f32 v178, v140, v178, 1.0
	v_fma_f32 v179, v140, v179, 1.0
	v_mul_f32_e32 v178, v178, v221
	v_mul_f32_e32 v180, v149, v176
	v_mul_f32_e32 v179, v179, v221
	v_mul_f32_e32 v181, v149, v177
	s_lshl_b32 s21, s56, 11
	s_add_u32 s21, s21, 0x2b441800
	v_add_u32_e32 v129, s21, v161
	global_store_dword v129, v174, s[96:97]
	s_lshl_b32 s21, s56, 11
	s_add_u32 s21, s21, 0x2d441800
	v_add_u32_e32 v129, s21, v161
	global_store_dword v129, v178, s[96:97]
	s_lshl_b32 s21, s56, 11
	s_add_u32 s21, s21, 0x2f441800
	v_add_u32_e32 v129, s21, v161
	global_store_dword v129, v180, s[96:97]
	s_lshl_b32 s21, s56, 11
	s_add_u32 s21, s21, 0x2c441800
	v_add_u32_e32 v129, s21, v161
	global_store_dword v129, v175, s[96:97]
	s_lshl_b32 s21, s56, 11
	s_add_u32 s21, s21, 0x2e441800
	v_add_u32_e32 v129, s21, v161
	global_store_dword v129, v179, s[96:97]
	s_lshl_b32 s21, s56, 11
	s_add_u32 s21, s21, 0x30441800
	v_add_u32_e32 v129, s21, v161
	global_store_dword v129, v181, s[96:97]
	v_mul_f32_e32 v182, v191, v178
	v_mul_f32_e32 v183, v191, v179
	v_mul_f32_e32 v157, v141, v182
	v_fmac_f32_e32 v157, v141, v183
	s_lshl_b32 s21, s56, 11
	s_add_u32 s21, s21, 0x28441800
	v_add_u32_e32 v129, s21, v161
	global_store_dword v129, v191, s[96:97]
	s_lshl_b32 s21, s56, 11
	s_add_u32 s21, s21, 0x29441800
	v_add_u32_e32 v129, s21, v161
	global_store_dword v129, v229, s[96:97]
	s_lshl_b32 s21, s56, 11
	s_add_u32 s21, s21, 0x2a441800
	v_add_u32_e32 v129, s21, v161
; template <bool RWONLY>
; __device__ __forceinline__ void phase_prep(const Params p, int l, char* smem) {
;     ...
;           float bsum = 0.f;
; #pragma unroll
;           for (int n = 0; n < 2; ++n) {
;             float zw = (n ? w0c1 : w0c0) + acc[tk][n][ch];
;             float za = (n ? a0c1 : a0c0) + acc[tk][2 + n][ch];
;             float dec = __expf(-0.6065306597126334f * sigmoidf_(zw));
;             float a = sigmoidf_(za);
;             float kd = k * (1.f + (a - 1.f) * kac);
;             float bb = kk * a;
;             size_t o = ((size_t)n * S_ + s) * 512 + c;
;             ((float*)(ws + OFF_SCW))[o] = dec;
;             ((float*)(ws + OFF_SCKD))[o] = kd;
;             ((float*)(ws + OFF_SCB))[o] = bb;
;             bsum += r * kd * rkc;
;           }
;           size_t o1 = (size_t)s * 512 + c;
;           ((float*)(ws + OFF_SCR))[o1] = r;
;           ((float*)(ws + OFF_SCV))[o1] = v;
;           ((float*)(ws + OFF_SCKK))[o1] = kk;
	global_store_dword v129, v149, s[96:97]
	v_add_f32_e32 v174, v142, v90
	v_add_f32_e32 v176, v144, v92
	v_add_f32_e32 v175, v143, v86
	v_add_f32_e32 v177, v145, v88
	v_mul_f32_e32 v174, 0xbfb8aa3b, v174
	v_mul_f32_e32 v175, 0xbfb8aa3b, v175
	v_mul_f32_e32 v176, 0xbfb8aa3b, v176
	v_mul_f32_e32 v177, 0xbfb8aa3b, v177
	v_exp_f32_e32 v174, v174
	v_exp_f32_e32 v175, v175
	v_exp_f32_e32 v176, v176
	v_exp_f32_e32 v177, v177
	s_nop 0
	v_add_f32_e32 v174, 1.0, v174
	v_add_f32_e32 v175, 1.0, v175
	v_add_f32_e32 v176, 1.0, v176
	v_add_f32_e32 v177, 1.0, v177
	v_rcp_f32_e32 v174, v174
	v_rcp_f32_e32 v175, v175
	v_rcp_f32_e32 v176, v176
	v_rcp_f32_e32 v177, v177
	s_nop 0
	v_mul_f32_e32 v174, 0xbf1b4598, v174
	v_mul_f32_e32 v175, 0xbf1b4598, v175
	v_mul_f32_e32 v174, 0x3fb8aa3b, v174
	v_mul_f32_e32 v175, 0x3fb8aa3b, v175
	v_exp_f32_e32 v174, v174
	v_exp_f32_e32 v175, v175
	v_add_f32_e32 v178, -1.0, v176
	v_add_f32_e32 v179, -1.0, v177
	v_fma_f32 v178, v140, v178, 1.0
	v_fma_f32 v179, v140, v179, 1.0
	v_mul_f32_e32 v178, v178, v222
	v_mul_f32_e32 v180, v150, v176
	v_mul_f32_e32 v179, v179, v222
	v_mul_f32_e32 v181, v150, v177
	s_lshl_b32 s21, s56, 11
	s_add_u32 s21, s21, 0x2b442000
	v_add_u32_e32 v129, s21, v161
	global_store_dword v129, v174, s[96:97]
	s_lshl_b32 s21, s56, 11
	s_add_u32 s21, s21, 0x2d442000
	v_add_u32_e32 v129, s21, v161
	global_store_dword v129, v178, s[96:97]
	s_lshl_b32 s21, s56, 11
	s_add_u32 s21, s21, 0x2f442000
	v_add_u32_e32 v129, s21, v161
	global_store_dword v129, v180, s[96:97]
	s_lshl_b32 s21, s56, 11
	s_add_u32 s21, s21, 0x2c442000
	v_add_u32_e32 v129, s21, v161
	global_store_dword v129, v175, s[96:97]
	s_lshl_b32 s21, s56, 11
	s_add_u32 s21, s21, 0x2e442000
	v_add_u32_e32 v129, s21, v161
	global_store_dword v129, v179, s[96:97]
	s_lshl_b32 s21, s56, 11
	s_add_u32 s21, s21, 0x30442000
	v_add_u32_e32 v129, s21, v161
	global_store_dword v129, v181, s[96:97]
	v_mul_f32_e32 v182, v214, v178
	v_mul_f32_e32 v183, v214, v179
	v_mul_f32_e32 v158, v141, v182
	v_fmac_f32_e32 v158, v141, v183
	s_lshl_b32 s21, s56, 11
	s_add_u32 s21, s21, 0x28442000
	v_add_u32_e32 v129, s21, v161
	global_store_dword v129, v214, s[96:97]
	s_lshl_b32 s21, s56, 11
	s_add_u32 s21, s21, 0x29442000
	v_add_u32_e32 v129, s21, v161
	global_store_dword v129, v230, s[96:97]
	s_lshl_b32 s21, s56, 11
	s_add_u32 s21, s21, 0x2a442000
	v_add_u32_e32 v129, s21, v161
	global_store_dword v129, v150, s[96:97]
	v_add_f32_e32 v174, v142, v82
	v_add_f32_e32 v176, v144, v84
	v_add_f32_e32 v175, v143, v78
	v_add_f32_e32 v177, v145, v80
	v_mul_f32_e32 v174, 0xbfb8aa3b, v174
	v_mul_f32_e32 v175, 0xbfb8aa3b, v175
	v_mul_f32_e32 v176, 0xbfb8aa3b, v176
	v_mul_f32_e32 v177, 0xbfb8aa3b, v177
	v_exp_f32_e32 v174, v174
	v_exp_f32_e32 v175, v175
	v_exp_f32_e32 v176, v176
	v_exp_f32_e32 v177, v177
	s_nop 0
	v_add_f32_e32 v174, 1.0, v174
	v_add_f32_e32 v175, 1.0, v175
	v_add_f32_e32 v176, 1.0, v176
	v_add_f32_e32 v177, 1.0, v177
	v_rcp_f32_e32 v174, v174
	v_rcp_f32_e32 v175, v175
	v_rcp_f32_e32 v176, v176
	v_rcp_f32_e32 v177, v177
	s_nop 0
	v_mul_f32_e32 v174, 0xbf1b4598, v174
	v_mul_f32_e32 v175, 0xbf1b4598, v175
	v_mul_f32_e32 v174, 0x3fb8aa3b, v174
	v_mul_f32_e32 v175, 0x3fb8aa3b, v175
	v_exp_f32_e32 v174, v174
	v_exp_f32_e32 v175, v175
	v_add_f32_e32 v178, -1.0, v176
	v_add_f32_e32 v179, -1.0, v177
	v_fma_f32 v178, v140, v178, 1.0
	v_fma_f32 v179, v140, v179, 1.0
	v_mul_f32_e32 v178, v178, v223
	v_mul_f32_e32 v180, v151, v176
	v_mul_f32_e32 v179, v179, v223
	v_mul_f32_e32 v181, v151, v177
	s_lshl_b32 s21, s56, 11
	s_add_u32 s21, s21, 0x2b442800
	v_add_u32_e32 v129, s21, v161
	global_store_dword v129, v174, s[96:97]
	s_lshl_b32 s21, s56, 11
	s_add_u32 s21, s21, 0x2d442800
	v_add_u32_e32 v129, s21, v161
	global_store_dword v129, v178, s[96:97]
	s_lshl_b32 s21, s56, 11
	s_add_u32 s21, s21, 0x2f442800
	v_add_u32_e32 v129, s21, v161
	global_store_dword v129, v180, s[96:97]
	s_lshl_b32 s21, s56, 11
	s_add_u32 s21, s21, 0x2c442800
	v_add_u32_e32 v129, s21, v161
	global_store_dword v129, v175, s[96:97]
	s_lshl_b32 s21, s56, 11
	s_add_u32 s21, s21, 0x2e442800
	v_add_u32_e32 v129, s21, v161
	global_store_dword v129, v179, s[96:97]
	s_lshl_b32 s21, s56, 11
	s_add_u32 s21, s21, 0x30442800
	v_add_u32_e32 v129, s21, v161
	global_store_dword v129, v181, s[96:97]
	v_mul_f32_e32 v182, v215, v178
	v_mul_f32_e32 v183, v215, v179
	v_mul_f32_e32 v159, v141, v182
	v_fmac_f32_e32 v159, v141, v183
	s_lshl_b32 s21, s56, 11
	s_add_u32 s21, s21, 0x28442800
	v_add_u32_e32 v129, s21, v161
	global_store_dword v129, v215, s[96:97]
	s_lshl_b32 s21, s56, 11
	s_add_u32 s21, s21, 0x29442800
	v_add_u32_e32 v129, s21, v161
	global_store_dword v129, v231, s[96:97]
	s_lshl_b32 s21, s56, 11
	s_add_u32 s21, s21, 0x2a442800
	v_add_u32_e32 v129, s21, v161
	global_store_dword v129, v151, s[96:97]
	v_add_f32_e32 v174, v142, v74
	v_add_f32_e32 v176, v144, v76
	v_add_f32_e32 v175, v143, v70
	v_add_f32_e32 v177, v145, v72
	v_mul_f32_e32 v174, 0xbfb8aa3b, v174
	v_mul_f32_e32 v175, 0xbfb8aa3b, v175
	v_mul_f32_e32 v176, 0xbfb8aa3b, v176
	v_mul_f32_e32 v177, 0xbfb8aa3b, v177
	v_exp_f32_e32 v174, v174
	v_exp_f32_e32 v175, v175
	v_exp_f32_e32 v176, v176
	v_exp_f32_e32 v177, v177
	s_nop 0
	v_add_f32_e32 v174, 1.0, v174
	v_add_f32_e32 v175, 1.0, v175
	v_add_f32_e32 v176, 1.0, v176
	v_add_f32_e32 v177, 1.0, v177
	v_rcp_f32_e32 v174, v174
	v_rcp_f32_e32 v175, v175
	v_rcp_f32_e32 v176, v176
	v_rcp_f32_e32 v177, v177
	s_nop 0
	v_mul_f32_e32 v174, 0xbf1b4598, v174
	v_mul_f32_e32 v175, 0xbf1b4598, v175
	v_mul_f32_e32 v174, 0x3fb8aa3b, v174
	v_mul_f32_e32 v175, 0x3fb8aa3b, v175
	v_exp_f32_e32 v174, v174
	v_exp_f32_e32 v175, v175
; template <bool RWONLY>
; __device__ __forceinline__ void phase_prep(const Params p, int l, char* smem) {
;     ...
;           float bsum = 0.f;
; #pragma unroll
;           for (int n = 0; n < 2; ++n) {
;             float zw = (n ? w0c1 : w0c0) + acc[tk][n][ch];
;             float za = (n ? a0c1 : a0c0) + acc[tk][2 + n][ch];
;             float dec = __expf(-0.6065306597126334f * sigmoidf_(zw));
;             float a = sigmoidf_(za);
;             float kd = k * (1.f + (a - 1.f) * kac);
;             float bb = kk * a;
;             size_t o = ((size_t)n * S_ + s) * 512 + c;
;             ((float*)(ws + OFF_SCW))[o] = dec;
;             ((float*)(ws + OFF_SCKD))[o] = kd;
;             ((float*)(ws + OFF_SCB))[o] = bb;
;             bsum += r * kd * rkc;
;           }
;           size_t o1 = (size_t)s * 512 + c;
;           ((float*)(ws + OFF_SCR))[o1] = r;
;           ((float*)(ws + OFF_SCV))[o1] = v;
;           ((float*)(ws + OFF_SCKK))[o1] = kk;
;           float bon = wave_sum(bsum);
;           if (lane == 0) ((float*)(ws + OFF_BONUS))[s * 8 + w + 4 * ch] = bon;
	v_add_f32_e32 v178, -1.0, v176
	v_add_f32_e32 v179, -1.0, v177
	v_fma_f32 v178, v140, v178, 1.0
	v_fma_f32 v179, v140, v179, 1.0
	v_mul_f32_e32 v178, v178, v224
	v_mul_f32_e32 v180, v152, v176
	v_mul_f32_e32 v179, v179, v224
	v_mul_f32_e32 v181, v152, v177
	s_lshl_b32 s21, s56, 11
	s_add_u32 s21, s21, 0x2b443000
	v_add_u32_e32 v129, s21, v161
	global_store_dword v129, v174, s[96:97]
	s_lshl_b32 s21, s56, 11
	s_add_u32 s21, s21, 0x2d443000
	v_add_u32_e32 v129, s21, v161
	global_store_dword v129, v178, s[96:97]
	s_lshl_b32 s21, s56, 11
	s_add_u32 s21, s21, 0x2f443000
	v_add_u32_e32 v129, s21, v161
	global_store_dword v129, v180, s[96:97]
	s_lshl_b32 s21, s56, 11
	s_add_u32 s21, s21, 0x2c443000
	v_add_u32_e32 v129, s21, v161
	global_store_dword v129, v175, s[96:97]
	s_lshl_b32 s21, s56, 11
	s_add_u32 s21, s21, 0x2e443000
	v_add_u32_e32 v129, s21, v161
	global_store_dword v129, v179, s[96:97]
	s_lshl_b32 s21, s56, 11
	s_add_u32 s21, s21, 0x30443000
	v_add_u32_e32 v129, s21, v161
	global_store_dword v129, v181, s[96:97]
	v_mul_f32_e32 v182, v216, v178
	v_mul_f32_e32 v183, v216, v179
	v_mul_f32_e32 v172, v141, v182
	v_fmac_f32_e32 v172, v141, v183
	s_lshl_b32 s21, s56, 11
	s_add_u32 s21, s21, 0x28443000
	v_add_u32_e32 v129, s21, v161
	global_store_dword v129, v216, s[96:97]
	s_lshl_b32 s21, s56, 11
	s_add_u32 s21, s21, 0x29443000
	v_add_u32_e32 v129, s21, v161
	global_store_dword v129, v232, s[96:97]
	s_lshl_b32 s21, s56, 11
	s_add_u32 s21, s21, 0x2a443000
	v_add_u32_e32 v129, s21, v161
	global_store_dword v129, v152, s[96:97]
	v_add_f32_e32 v174, v142, v66
	v_add_f32_e32 v176, v144, v68
	v_add_f32_e32 v175, v143, v62
	v_add_f32_e32 v177, v145, v64
	v_mul_f32_e32 v174, 0xbfb8aa3b, v174
	v_mul_f32_e32 v175, 0xbfb8aa3b, v175
	v_mul_f32_e32 v176, 0xbfb8aa3b, v176
	v_mul_f32_e32 v177, 0xbfb8aa3b, v177
	v_exp_f32_e32 v174, v174
	v_exp_f32_e32 v175, v175
	v_exp_f32_e32 v176, v176
	v_exp_f32_e32 v177, v177
	s_nop 0
	v_add_f32_e32 v174, 1.0, v174
	v_add_f32_e32 v175, 1.0, v175
	v_add_f32_e32 v176, 1.0, v176
	v_add_f32_e32 v177, 1.0, v177
	v_rcp_f32_e32 v174, v174
	v_rcp_f32_e32 v175, v175
	v_rcp_f32_e32 v176, v176
	v_rcp_f32_e32 v177, v177
	s_nop 0
	v_mul_f32_e32 v174, 0xbf1b4598, v174
	v_mul_f32_e32 v175, 0xbf1b4598, v175
	v_mul_f32_e32 v174, 0x3fb8aa3b, v174
	v_mul_f32_e32 v175, 0x3fb8aa3b, v175
	v_exp_f32_e32 v174, v174
	v_exp_f32_e32 v175, v175
	v_add_f32_e32 v178, -1.0, v176
	v_add_f32_e32 v179, -1.0, v177
	v_fma_f32 v178, v140, v178, 1.0
	v_fma_f32 v179, v140, v179, 1.0
	v_mul_f32_e32 v178, v178, v225
	v_mul_f32_e32 v180, v153, v176
	v_mul_f32_e32 v179, v179, v225
	v_mul_f32_e32 v181, v153, v177
	s_lshl_b32 s21, s56, 11
	s_add_u32 s21, s21, 0x2b443800
	v_add_u32_e32 v129, s21, v161
	global_store_dword v129, v174, s[96:97]
	s_lshl_b32 s21, s56, 11
	s_add_u32 s21, s21, 0x2d443800
	v_add_u32_e32 v129, s21, v161
	global_store_dword v129, v178, s[96:97]
	s_lshl_b32 s21, s56, 11
	s_add_u32 s21, s21, 0x2f443800
	v_add_u32_e32 v129, s21, v161
	global_store_dword v129, v180, s[96:97]
	s_lshl_b32 s21, s56, 11
	s_add_u32 s21, s21, 0x2c443800
	v_add_u32_e32 v129, s21, v161
	global_store_dword v129, v175, s[96:97]
	s_lshl_b32 s21, s56, 11
	s_add_u32 s21, s21, 0x2e443800
	v_add_u32_e32 v129, s21, v161
	global_store_dword v129, v179, s[96:97]
	s_lshl_b32 s21, s56, 11
	s_add_u32 s21, s21, 0x30443800
	v_add_u32_e32 v129, s21, v161
	global_store_dword v129, v181, s[96:97]
	v_mul_f32_e32 v182, v217, v178
	v_mul_f32_e32 v183, v217, v179
	v_mul_f32_e32 v173, v141, v182
	v_fmac_f32_e32 v173, v141, v183
	s_lshl_b32 s21, s56, 11
	s_add_u32 s21, s21, 0x28443800
	v_add_u32_e32 v129, s21, v161
	global_store_dword v129, v217, s[96:97]
	s_lshl_b32 s21, s56, 11
	s_add_u32 s21, s21, 0x29443800
	v_add_u32_e32 v129, s21, v161
	global_store_dword v129, v233, s[96:97]
	s_lshl_b32 s21, s56, 11
	s_add_u32 s21, s21, 0x2a443800
	v_add_u32_e32 v129, s21, v161
	global_store_dword v129, v153, s[96:97]
	v_add_f32_dpp v154, v154, v154 quad_perm:[1,0,3,2] row_mask:0xf bank_mask:0xf bound_ctrl:1
	v_add_f32_dpp v155, v155, v155 quad_perm:[1,0,3,2] row_mask:0xf bank_mask:0xf bound_ctrl:1
	v_add_f32_dpp v156, v156, v156 quad_perm:[1,0,3,2] row_mask:0xf bank_mask:0xf bound_ctrl:1
	v_add_f32_dpp v157, v157, v157 quad_perm:[1,0,3,2] row_mask:0xf bank_mask:0xf bound_ctrl:1
	v_add_f32_dpp v158, v158, v158 quad_perm:[1,0,3,2] row_mask:0xf bank_mask:0xf bound_ctrl:1
	v_add_f32_dpp v159, v159, v159 quad_perm:[1,0,3,2] row_mask:0xf bank_mask:0xf bound_ctrl:1
	v_add_f32_dpp v172, v172, v172 quad_perm:[1,0,3,2] row_mask:0xf bank_mask:0xf bound_ctrl:1
	v_add_f32_dpp v173, v173, v173 quad_perm:[1,0,3,2] row_mask:0xf bank_mask:0xf bound_ctrl:1
	v_add_f32_dpp v154, v154, v154 quad_perm:[2,3,0,1] row_mask:0xf bank_mask:0xf bound_ctrl:1
	v_add_f32_dpp v155, v155, v155 quad_perm:[2,3,0,1] row_mask:0xf bank_mask:0xf bound_ctrl:1
	v_add_f32_dpp v156, v156, v156 quad_perm:[2,3,0,1] row_mask:0xf bank_mask:0xf bound_ctrl:1
	v_add_f32_dpp v157, v157, v157 quad_perm:[2,3,0,1] row_mask:0xf bank_mask:0xf bound_ctrl:1
	v_add_f32_dpp v158, v158, v158 quad_perm:[2,3,0,1] row_mask:0xf bank_mask:0xf bound_ctrl:1
	v_add_f32_dpp v159, v159, v159 quad_perm:[2,3,0,1] row_mask:0xf bank_mask:0xf bound_ctrl:1
	v_add_f32_dpp v172, v172, v172 quad_perm:[2,3,0,1] row_mask:0xf bank_mask:0xf bound_ctrl:1
	v_add_f32_dpp v173, v173, v173 quad_perm:[2,3,0,1] row_mask:0xf bank_mask:0xf bound_ctrl:1
	v_add_f32_dpp v154, v154, v154 row_half_mirror row_mask:0xf bank_mask:0xf bound_ctrl:1
	v_add_f32_dpp v155, v155, v155 row_half_mirror row_mask:0xf bank_mask:0xf bound_ctrl:1
	v_add_f32_dpp v156, v156, v156 row_half_mirror row_mask:0xf bank_mask:0xf bound_ctrl:1
; template <bool RWONLY>
; __device__ __forceinline__ void phase_prep(const Params p, int l, char* smem) {
;     ...
;       for (int ch = 0; ch < 2; ++ch) {
;         const int c = tid + ch * 256;
;         float shc[3][3];
; #pragma unroll
;         for (int q = 0; q < 3; ++q)
; #pragma unroll
;           for (int j = 0; j < 3; ++j) shc[q][j] = sh[j * 1792 + q * 512 + c];
;         const float kkc = kkp[c], kac = kap[c], rkc = rkp[c];
;         const float w0c0 = w0[c], w0c1 = w0[512 + c], a0c0 = a0[c], a0c1 = a0[512 + c];
;         float um[3], u0[3];
; #pragma unroll
;         for (int q = 0; q < 3; ++q) {
;           um[q] = s0 > 0 ? RWU[(size_t)(s0 - 1) * 1792 + q * 512 + c] : 0.f;
;           u0[q] = RWU[(size_t)s0 * 1792 + q * 512 + c];
;         }
;     ...
;           float bon = wave_sum(bsum);
;           if (lane == 0) ((float*)(ws + OFF_BONUS))[s * 8 + w + 4 * ch] = bon;
	v_add_f32_dpp v157, v157, v157 row_half_mirror row_mask:0xf bank_mask:0xf bound_ctrl:1
	v_add_f32_dpp v158, v158, v158 row_half_mirror row_mask:0xf bank_mask:0xf bound_ctrl:1
	v_add_f32_dpp v159, v159, v159 row_half_mirror row_mask:0xf bank_mask:0xf bound_ctrl:1
	v_add_f32_dpp v172, v172, v172 row_half_mirror row_mask:0xf bank_mask:0xf bound_ctrl:1
	v_add_f32_dpp v173, v173, v173 row_half_mirror row_mask:0xf bank_mask:0xf bound_ctrl:1
	v_add_f32_dpp v154, v154, v154 row_mirror row_mask:0xf bank_mask:0xf bound_ctrl:1
	v_add_f32_dpp v155, v155, v155 row_mirror row_mask:0xf bank_mask:0xf bound_ctrl:1
	v_add_f32_dpp v156, v156, v156 row_mirror row_mask:0xf bank_mask:0xf bound_ctrl:1
	v_add_f32_dpp v157, v157, v157 row_mirror row_mask:0xf bank_mask:0xf bound_ctrl:1
	v_add_f32_dpp v158, v158, v158 row_mirror row_mask:0xf bank_mask:0xf bound_ctrl:1
	v_add_f32_dpp v159, v159, v159 row_mirror row_mask:0xf bank_mask:0xf bound_ctrl:1
	v_add_f32_dpp v172, v172, v172 row_mirror row_mask:0xf bank_mask:0xf bound_ctrl:1
	v_add_f32_dpp v173, v173, v173 row_mirror row_mask:0xf bank_mask:0xf bound_ctrl:1
	ds_bpermute_b32 v174, v163, v154
	ds_bpermute_b32 v175, v163, v155
	ds_bpermute_b32 v176, v163, v156
	ds_bpermute_b32 v177, v163, v157
	ds_bpermute_b32 v178, v163, v158
	ds_bpermute_b32 v179, v163, v159
	ds_bpermute_b32 v180, v163, v172
	ds_bpermute_b32 v181, v163, v173
	s_waitcnt lgkmcnt(0)
	v_add_f32_e32 v154, v154, v174
	v_add_f32_e32 v155, v155, v175
	v_add_f32_e32 v156, v156, v176
	v_add_f32_e32 v157, v157, v177
	v_add_f32_e32 v158, v158, v178
	v_add_f32_e32 v159, v159, v179
	v_add_f32_e32 v172, v172, v180
	v_add_f32_e32 v173, v173, v181
	ds_bpermute_b32 v174, v162, v154
	ds_bpermute_b32 v175, v162, v155
	ds_bpermute_b32 v176, v162, v156
	ds_bpermute_b32 v177, v162, v157
	ds_bpermute_b32 v178, v162, v158
	ds_bpermute_b32 v179, v162, v159
	ds_bpermute_b32 v180, v162, v172
	ds_bpermute_b32 v181, v162, v173
	s_waitcnt lgkmcnt(0)
	v_add_f32_e32 v154, v154, v174
	v_add_f32_e32 v155, v155, v175
	v_add_f32_e32 v156, v156, v176
	v_add_f32_e32 v157, v157, v177
	v_add_f32_e32 v158, v158, v178
	v_add_f32_e32 v159, v159, v179
	v_add_f32_e32 v172, v172, v180
	v_add_f32_e32 v173, v173, v181
	s_and_saveexec_b64 s[2:3], s[40:41]
	s_lshl_b32 s21, s56, 5
	s_add_u32 s21, s21, 0x31440000
	v_add_u32_e32 v129, s21, v126
	global_store_dword v129, v154, s[96:97]
	s_lshl_b32 s21, s56, 5
	s_add_u32 s21, s21, 0x31440020
	v_add_u32_e32 v129, s21, v126
	global_store_dword v129, v155, s[96:97]
	s_lshl_b32 s21, s56, 5
	s_add_u32 s21, s21, 0x31440040
	v_add_u32_e32 v129, s21, v126
	global_store_dword v129, v156, s[96:97]
	s_lshl_b32 s21, s56, 5
	s_add_u32 s21, s21, 0x31440060
	v_add_u32_e32 v129, s21, v126
	global_store_dword v129, v157, s[96:97]
	s_lshl_b32 s21, s56, 5
	s_add_u32 s21, s21, 0x31440080
	v_add_u32_e32 v129, s21, v126
	global_store_dword v129, v158, s[96:97]
	s_lshl_b32 s21, s56, 5
	s_add_u32 s21, s21, 0x314400a0
	v_add_u32_e32 v129, s21, v126
	global_store_dword v129, v159, s[96:97]
	s_lshl_b32 s21, s56, 5
	s_add_u32 s21, s21, 0x314400c0
	v_add_u32_e32 v129, s21, v126
	global_store_dword v129, v172, s[96:97]
	s_lshl_b32 s21, s56, 5
	s_add_u32 s21, s21, 0x314400e0
	v_add_u32_e32 v129, s21, v126
	global_store_dword v129, v173, s[96:97]
	s_mov_b64 exec, s[2:3]
	global_load_dword v130, v[2:3], off offset:1024
	global_load_dword v131, v[14:15], off offset:1024
	global_load_dword v132, v[16:17], off offset:1024
	global_load_dword v133, v[2:3], off offset:3072
	global_load_dword v134, v[18:19], off offset:1024
	global_load_dword v135, v[20:21], off offset:1024
	global_load_dword v136, v[22:23], off offset:1024
	global_load_dword v137, v[24:25], off offset:1024
	global_load_dword v138, v[26:27], off offset:1024
	global_load_dword v139, v[28:29], off offset:1024
	global_load_dword v140, v[30:31], off offset:1024
	global_load_dword v141, v[32:33], off offset:1024
	global_load_dword v142, v[34:35], off offset:1024
	global_load_dword v143, v[34:35], off offset:3072
	global_load_dword v144, v[36:37], off offset:1024
	global_load_dword v145, v[36:37], off offset:3072
	s_add_i32 s20, s56, -1
	s_max_i32 s20, s20, 0
	s_mul_i32 s21, s20, 0x1c00
	s_add_u32 s21, s21, 0x24c40400
	v_add_u32_e32 v127, s21, v161
	v_add_u32_e32 v128, 0x1000, v127
	global_load_dword v146, v127, s[96:97]
	global_load_dword v147, v127, s[96:97] offset:2048
	global_load_dword v148, v128, s[96:97]
	s_add_i32 s20, s56, 0
	s_mul_i32 s21, s20, 0x1c00
	s_add_u32 s21, s21, 0x24c40400
	v_add_u32_e32 v127, s21, v161
	v_add_u32_e32 v128, 0x1000, v127
	global_load_dword v149, v127, s[96:97]
	global_load_dword v150, v127, s[96:97] offset:2048
	global_load_dword v151, v128, s[96:97]
	s_add_i32 s20, s56, 1
	s_mul_i32 s21, s20, 0x1c00
	s_add_u32 s21, s21, 0x24c40400
	v_add_u32_e32 v127, s21, v161
	v_add_u32_e32 v128, 0x1000, v127
	global_load_dword v152, v127, s[96:97]
	global_load_dword v153, v127, s[96:97] offset:2048
	global_load_dword v154, v128, s[96:97]
	s_add_i32 s20, s56, 2
	s_mul_i32 s21, s20, 0x1c00
	s_add_u32 s21, s21, 0x24c40400
	v_add_u32_e32 v127, s21, v161
	v_add_u32_e32 v128, 0x1000, v127
	global_load_dword v155, v127, s[96:97]
	global_load_dword v156, v127, s[96:97] offset:2048
	global_load_dword v157, v128, s[96:97]
	s_add_i32 s20, s56, 3
	s_mul_i32 s21, s20, 0x1c00
	s_add_u32 s21, s21, 0x24c40400
	v_add_u32_e32 v127, s21, v161
	v_add_u32_e32 v128, 0x1000, v127
	global_load_dword v158, v127, s[96:97]
	global_load_dword v159, v127, s[96:97] offset:2048
	global_load_dword v172, v128, s[96:97]
	s_add_i32 s20, s56, 4
	s_mul_i32 s21, s20, 0x1c00
	s_add_u32 s21, s21, 0x24c40400
	v_add_u32_e32 v127, s21, v161
	v_add_u32_e32 v128, 0x1000, v127
	global_load_dword v173, v127, s[96:97]
	global_load_dword v174, v127, s[96:97] offset:2048
	global_load_dword v175, v128, s[96:97]
	s_add_i32 s20, s56, 5
	s_mul_i32 s21, s20, 0x1c00
	s_add_u32 s21, s21, 0x24c40400
	v_add_u32_e32 v127, s21, v161
	v_add_u32_e32 v128, 0x1000, v127
	global_load_dword v176, v127, s[96:97]
	global_load_dword v177, v127, s[96:97] offset:2048
	global_load_dword v178, v128, s[96:97]
	s_add_i32 s20, s56, 6
	s_mul_i32 s21, s20, 0x1c00
	s_add_u32 s21, s21, 0x24c40400
	v_add_u32_e32 v127, s21, v161
	v_add_u32_e32 v128, 0x1000, v127
	global_load_dword v179, v127, s[96:97]
	global_load_dword v180, v127, s[96:97] offset:2048
	global_load_dword v181, v128, s[96:97]
	s_add_i32 s20, s56, 7
	s_mul_i32 s21, s20, 0x1c00
	s_add_u32 s21, s21, 0x24c40400
	v_add_u32_e32 v127, s21, v161
	v_add_u32_e32 v128, 0x1000, v127
	global_load_dword v182, v127, s[96:97]
	global_load_dword v183, v127, s[96:97] offset:2048
	global_load_dword v184, v128, s[96:97]
	s_add_i32 s20, s56, 8
	s_min_i32 s20, s20, 0x1fff
	s_mul_i32 s21, s20, 0x1c00
	s_add_u32 s21, s21, 0x24c40400
	v_add_u32_e32 v127, s21, v161
	v_add_u32_e32 v128, 0x1000, v127
	global_load_dword v185, v127, s[96:97]
	global_load_dword v186, v127, s[96:97] offset:2048
	global_load_dword v187, v128, s[96:97]
	s_waitcnt vmcnt(0)
; template <bool RWONLY>
; __device__ __forceinline__ void phase_prep(const Params p, int l, char* smem) {
;     ...
;         for (int q = 0; q < 3; ++q) {
;           um[q] = s0 > 0 ? RWU[(size_t)(s0 - 1) * 1792 + q * 512 + c] : 0.f;
;           u0[q] = RWU[(size_t)s0 * 1792 + q * 512 + c];
;         }
; #pragma unroll
;         for (int tk = 0; tk < 8; ++tk) {
;           const int s = s0 + tk;
;           float rkv[3];
; #pragma unroll
;           for (int q = 0; q < 3; ++q) {
;             float up = s < S_ - 1 ? RWU[(size_t)(s + 1) * 1792 + q * 512 + c] : 0.f;
;             rkv[q] = shc[q][0] * um[q] + shc[q][1] * u0[q] + shc[q][2] * up;
;             um[q] = u0[q];
;             u0[q] = up;
;           }
;           float r = rkv[0], k = rkv[1], v = rkv[2];
;           float kkr = k * kkc;
;           float ss = wave_sum(kkr * kkr);
	v_mul_f32_e32 v146, s24, v146
	v_mul_f32_e32 v185, s25, v185
	v_mul_f32_e32 v147, s24, v147
	v_mul_f32_e32 v186, s25, v186
	v_mul_f32_e32 v148, s24, v148
	v_mul_f32_e32 v187, s25, v187
	v_mul_f32_e32 v188, v130, v146
	v_mul_f32_e32 v218, v133, v147
	v_mul_f32_e32 v226, v136, v148
	v_fmac_f32_e32 v188, v131, v149
	v_fmac_f32_e32 v218, v134, v150
	v_fmac_f32_e32 v226, v137, v151
	v_fmac_f32_e32 v188, v132, v152
	v_fmac_f32_e32 v218, v135, v153
	v_fmac_f32_e32 v226, v138, v154
	v_mul_f32_e32 v189, v130, v149
	v_mul_f32_e32 v219, v133, v150
	v_mul_f32_e32 v227, v136, v151
	v_fmac_f32_e32 v189, v131, v152
	v_fmac_f32_e32 v219, v134, v153
	v_fmac_f32_e32 v227, v137, v154
	v_fmac_f32_e32 v189, v132, v155
	v_fmac_f32_e32 v219, v135, v156
	v_fmac_f32_e32 v227, v138, v157
	v_mul_f32_e32 v190, v130, v152
	v_mul_f32_e32 v220, v133, v153
	v_mul_f32_e32 v228, v136, v154
	v_fmac_f32_e32 v190, v131, v155
	v_fmac_f32_e32 v220, v134, v156
	v_fmac_f32_e32 v228, v137, v157
	v_fmac_f32_e32 v190, v132, v158
	v_fmac_f32_e32 v220, v135, v159
	v_fmac_f32_e32 v228, v138, v172
	v_mul_f32_e32 v191, v130, v155
	v_mul_f32_e32 v221, v133, v156
	v_mul_f32_e32 v229, v136, v157
	v_fmac_f32_e32 v191, v131, v158
	v_fmac_f32_e32 v221, v134, v159
	v_fmac_f32_e32 v229, v137, v172
	v_fmac_f32_e32 v191, v132, v173
	v_fmac_f32_e32 v221, v135, v174
	v_fmac_f32_e32 v229, v138, v175
	v_mul_f32_e32 v214, v130, v158
	v_mul_f32_e32 v222, v133, v159
	v_mul_f32_e32 v230, v136, v172
	v_fmac_f32_e32 v214, v131, v173
	v_fmac_f32_e32 v222, v134, v174
	v_fmac_f32_e32 v230, v137, v175
	v_fmac_f32_e32 v214, v132, v176
	v_fmac_f32_e32 v222, v135, v177
	v_fmac_f32_e32 v230, v138, v178
	v_mul_f32_e32 v215, v130, v173
	v_mul_f32_e32 v223, v133, v174
	v_mul_f32_e32 v231, v136, v175
	v_fmac_f32_e32 v215, v131, v176
	v_fmac_f32_e32 v223, v134, v177
	v_fmac_f32_e32 v231, v137, v178
	v_fmac_f32_e32 v215, v132, v179
	v_fmac_f32_e32 v223, v135, v180
	v_fmac_f32_e32 v231, v138, v181
	v_mul_f32_e32 v216, v130, v176
	v_mul_f32_e32 v224, v133, v177
	v_mul_f32_e32 v232, v136, v178
	v_fmac_f32_e32 v216, v131, v179
	v_fmac_f32_e32 v224, v134, v180
	v_fmac_f32_e32 v232, v137, v181
	v_fmac_f32_e32 v216, v132, v182
	v_fmac_f32_e32 v224, v135, v183
	v_fmac_f32_e32 v232, v138, v184
	v_mul_f32_e32 v217, v130, v179
	v_mul_f32_e32 v225, v133, v180
	v_mul_f32_e32 v233, v136, v181
	v_fmac_f32_e32 v217, v131, v182
	v_fmac_f32_e32 v225, v134, v183
	v_fmac_f32_e32 v233, v137, v184
	v_fmac_f32_e32 v217, v132, v185
	v_fmac_f32_e32 v225, v135, v186
	v_fmac_f32_e32 v233, v138, v187
	v_mul_f32_e32 v146, v218, v139
	v_mul_f32_e32 v147, v219, v139
	v_mul_f32_e32 v148, v220, v139
	v_mul_f32_e32 v149, v221, v139
	v_mul_f32_e32 v150, v222, v139
	v_mul_f32_e32 v151, v223, v139
	v_mul_f32_e32 v152, v224, v139
	v_mul_f32_e32 v153, v225, v139
	v_mul_f32_e32 v154, v146, v146
	v_mul_f32_e32 v155, v147, v147
	v_mul_f32_e32 v156, v148, v148
	v_mul_f32_e32 v157, v149, v149
	v_mul_f32_e32 v158, v150, v150
	v_mul_f32_e32 v159, v151, v151
	v_mul_f32_e32 v172, v152, v152
	v_mul_f32_e32 v173, v153, v153
	v_add_f32_dpp v154, v154, v154 quad_perm:[1,0,3,2] row_mask:0xf bank_mask:0xf bound_ctrl:1
	v_add_f32_dpp v155, v155, v155 quad_perm:[1,0,3,2] row_mask:0xf bank_mask:0xf bound_ctrl:1
	v_add_f32_dpp v156, v156, v156 quad_perm:[1,0,3,2] row_mask:0xf bank_mask:0xf bound_ctrl:1
	v_add_f32_dpp v157, v157, v157 quad_perm:[1,0,3,2] row_mask:0xf bank_mask:0xf bound_ctrl:1
	v_add_f32_dpp v158, v158, v158 quad_perm:[1,0,3,2] row_mask:0xf bank_mask:0xf bound_ctrl:1
	v_add_f32_dpp v159, v159, v159 quad_perm:[1,0,3,2] row_mask:0xf bank_mask:0xf bound_ctrl:1
	v_add_f32_dpp v172, v172, v172 quad_perm:[1,0,3,2] row_mask:0xf bank_mask:0xf bound_ctrl:1
	v_add_f32_dpp v173, v173, v173 quad_perm:[1,0,3,2] row_mask:0xf bank_mask:0xf bound_ctrl:1
	v_add_f32_dpp v154, v154, v154 quad_perm:[2,3,0,1] row_mask:0xf bank_mask:0xf bound_ctrl:1
	v_add_f32_dpp v155, v155, v155 quad_perm:[2,3,0,1] row_mask:0xf bank_mask:0xf bound_ctrl:1
	v_add_f32_dpp v156, v156, v156 quad_perm:[2,3,0,1] row_mask:0xf bank_mask:0xf bound_ctrl:1
	v_add_f32_dpp v157, v157, v157 quad_perm:[2,3,0,1] row_mask:0xf bank_mask:0xf bound_ctrl:1
	v_add_f32_dpp v158, v158, v158 quad_perm:[2,3,0,1] row_mask:0xf bank_mask:0xf bound_ctrl:1
	v_add_f32_dpp v159, v159, v159 quad_perm:[2,3,0,1] row_mask:0xf bank_mask:0xf bound_ctrl:1
	v_add_f32_dpp v172, v172, v172 quad_perm:[2,3,0,1] row_mask:0xf bank_mask:0xf bound_ctrl:1
	v_add_f32_dpp v173, v173, v173 quad_perm:[2,3,0,1] row_mask:0xf bank_mask:0xf bound_ctrl:1
	v_add_f32_dpp v154, v154, v154 row_half_mirror row_mask:0xf bank_mask:0xf bound_ctrl:1
	v_add_f32_dpp v155, v155, v155 row_half_mirror row_mask:0xf bank_mask:0xf bound_ctrl:1
	v_add_f32_dpp v156, v156, v156 row_half_mirror row_mask:0xf bank_mask:0xf bound_ctrl:1
	v_add_f32_dpp v157, v157, v157 row_half_mirror row_mask:0xf bank_mask:0xf bound_ctrl:1
	v_add_f32_dpp v158, v158, v158 row_half_mirror row_mask:0xf bank_mask:0xf bound_ctrl:1
	v_add_f32_dpp v159, v159, v159 row_half_mirror row_mask:0xf bank_mask:0xf bound_ctrl:1
	v_add_f32_dpp v172, v172, v172 row_half_mirror row_mask:0xf bank_mask:0xf bound_ctrl:1
	v_add_f32_dpp v173, v173, v173 row_half_mirror row_mask:0xf bank_mask:0xf bound_ctrl:1
	v_add_f32_dpp v154, v154, v154 row_mirror row_mask:0xf bank_mask:0xf bound_ctrl:1
	v_add_f32_dpp v155, v155, v155 row_mirror row_mask:0xf bank_mask:0xf bound_ctrl:1
	v_add_f32_dpp v156, v156, v156 row_mirror row_mask:0xf bank_mask:0xf bound_ctrl:1
	v_add_f32_dpp v157, v157, v157 row_mirror row_mask:0xf bank_mask:0xf bound_ctrl:1
	v_add_f32_dpp v158, v158, v158 row_mirror row_mask:0xf bank_mask:0xf bound_ctrl:1
	v_add_f32_dpp v159, v159, v159 row_mirror row_mask:0xf bank_mask:0xf bound_ctrl:1
	v_add_f32_dpp v172, v172, v172 row_mirror row_mask:0xf bank_mask:0xf bound_ctrl:1
	v_add_f32_dpp v173, v173, v173 row_mirror row_mask:0xf bank_mask:0xf bound_ctrl:1
	ds_bpermute_b32 v174, v163, v154
	ds_bpermute_b32 v175, v163, v155
	ds_bpermute_b32 v176, v163, v156
	ds_bpermute_b32 v177, v163, v157
	ds_bpermute_b32 v178, v163, v158
	ds_bpermute_b32 v179, v163, v159
	ds_bpermute_b32 v180, v163, v172
	ds_bpermute_b32 v181, v163, v173
	s_waitcnt lgkmcnt(0)
; template <bool RWONLY>
; __device__ __forceinline__ void phase_prep(const Params p, int l, char* smem) {
;     ...
;           float kkr = k * kkc;
;           float ss = wave_sum(kkr * kkr);
;           float kk = kkr * __builtin_amdgcn_rcpf(fmaxf(__builtin_amdgcn_sqrtf(ss), 1e-12f));
;           float bsum = 0.f;
; #pragma unroll
;           for (int n = 0; n < 2; ++n) {
;             float zw = (n ? w0c1 : w0c0) + acc[tk][n][ch];
;             float za = (n ? a0c1 : a0c0) + acc[tk][2 + n][ch];
;             float dec = __expf(-0.6065306597126334f * sigmoidf_(zw));
;             float a = sigmoidf_(za);
;             float kd = k * (1.f + (a - 1.f) * kac);
;             float bb = kk * a;
;             size_t o = ((size_t)n * S_ + s) * 512 + c;
;             ((float*)(ws + OFF_SCW))[o] = dec;
;             ((float*)(ws + OFF_SCKD))[o] = kd;
;             ((float*)(ws + OFF_SCB))[o] = bb;
;             bsum += r * kd * rkc;
;           }
;           size_t o1 = (size_t)s * 512 + c;
;           ((float*)(ws + OFF_SCR))[o1] = r;
;           ((float*)(ws + OFF_SCV))[o1] = v;
;           ((float*)(ws + OFF_SCKK))[o1] = kk;
	v_add_f32_e32 v154, v154, v174
	v_add_f32_e32 v155, v155, v175
	v_add_f32_e32 v156, v156, v176
	v_add_f32_e32 v157, v157, v177
	v_add_f32_e32 v158, v158, v178
	v_add_f32_e32 v159, v159, v179
	v_add_f32_e32 v172, v172, v180
	v_add_f32_e32 v173, v173, v181
	ds_bpermute_b32 v174, v162, v154
	ds_bpermute_b32 v175, v162, v155
	ds_bpermute_b32 v176, v162, v156
	ds_bpermute_b32 v177, v162, v157
	ds_bpermute_b32 v178, v162, v158
	ds_bpermute_b32 v179, v162, v159
	ds_bpermute_b32 v180, v162, v172
	ds_bpermute_b32 v181, v162, v173
	s_waitcnt lgkmcnt(0)
	v_add_f32_e32 v154, v154, v174
	v_add_f32_e32 v155, v155, v175
	v_add_f32_e32 v156, v156, v176
	v_add_f32_e32 v157, v157, v177
	v_add_f32_e32 v158, v158, v178
	v_add_f32_e32 v159, v159, v179
	v_add_f32_e32 v172, v172, v180
	v_add_f32_e32 v173, v173, v181
	v_sqrt_f32_e32 v154, v154
	v_sqrt_f32_e32 v155, v155
	v_sqrt_f32_e32 v156, v156
	v_sqrt_f32_e32 v157, v157
	v_sqrt_f32_e32 v158, v158
	v_sqrt_f32_e32 v159, v159
	v_sqrt_f32_e32 v172, v172
	v_sqrt_f32_e32 v173, v173
	v_max_f32_e32 v154, 0x2b8cbccc, v154
	v_max_f32_e32 v155, 0x2b8cbccc, v155
	v_max_f32_e32 v156, 0x2b8cbccc, v156
	v_max_f32_e32 v157, 0x2b8cbccc, v157
	v_max_f32_e32 v158, 0x2b8cbccc, v158
	v_max_f32_e32 v159, 0x2b8cbccc, v159
	v_max_f32_e32 v172, 0x2b8cbccc, v172
	v_max_f32_e32 v173, 0x2b8cbccc, v173
	v_rcp_f32_e32 v154, v154
	v_rcp_f32_e32 v155, v155
	v_rcp_f32_e32 v156, v156
	v_rcp_f32_e32 v157, v157
	v_rcp_f32_e32 v158, v158
	v_rcp_f32_e32 v159, v159
	v_rcp_f32_e32 v172, v172
	v_rcp_f32_e32 v173, v173
	s_nop 0
	v_mul_f32_e32 v146, v146, v154
	v_mul_f32_e32 v147, v147, v155
	v_mul_f32_e32 v148, v148, v156
	v_mul_f32_e32 v149, v149, v157
	v_mul_f32_e32 v150, v150, v158
	v_mul_f32_e32 v151, v151, v159
	v_mul_f32_e32 v152, v152, v172
	v_mul_f32_e32 v153, v153, v173
	v_add_f32_e32 v174, v142, v124
	v_add_f32_e32 v176, v144, v122
	v_add_f32_e32 v175, v143, v120
	v_add_f32_e32 v177, v145, v118
	v_mul_f32_e32 v174, 0xbfb8aa3b, v174
	v_mul_f32_e32 v175, 0xbfb8aa3b, v175
	v_mul_f32_e32 v176, 0xbfb8aa3b, v176
	v_mul_f32_e32 v177, 0xbfb8aa3b, v177
	v_exp_f32_e32 v174, v174
	v_exp_f32_e32 v175, v175
	v_exp_f32_e32 v176, v176
	v_exp_f32_e32 v177, v177
	s_nop 0
	v_add_f32_e32 v174, 1.0, v174
	v_add_f32_e32 v175, 1.0, v175
	v_add_f32_e32 v176, 1.0, v176
	v_add_f32_e32 v177, 1.0, v177
	v_rcp_f32_e32 v174, v174
	v_rcp_f32_e32 v175, v175
	v_rcp_f32_e32 v176, v176
	v_rcp_f32_e32 v177, v177
	s_nop 0
	v_mul_f32_e32 v174, 0xbf1b4598, v174
	v_mul_f32_e32 v175, 0xbf1b4598, v175
	v_mul_f32_e32 v174, 0x3fb8aa3b, v174
	v_mul_f32_e32 v175, 0x3fb8aa3b, v175
	v_exp_f32_e32 v174, v174
	v_exp_f32_e32 v175, v175
	v_add_f32_e32 v178, -1.0, v176
	v_add_f32_e32 v179, -1.0, v177
	v_fma_f32 v178, v140, v178, 1.0
	v_fma_f32 v179, v140, v179, 1.0
	v_mul_f32_e32 v178, v178, v218
	v_mul_f32_e32 v180, v146, v176
	v_mul_f32_e32 v179, v179, v218
	v_mul_f32_e32 v181, v146, v177
	s_lshl_b32 s21, s56, 11
	s_add_u32 s21, s21, 0x2b440400
	v_add_u32_e32 v129, s21, v161
	global_store_dword v129, v174, s[96:97]
	s_lshl_b32 s21, s56, 11
	s_add_u32 s21, s21, 0x2d440400
	v_add_u32_e32 v129, s21, v161
	global_store_dword v129, v178, s[96:97]
	s_lshl_b32 s21, s56, 11
	s_add_u32 s21, s21, 0x2f440400
	v_add_u32_e32 v129, s21, v161
	global_store_dword v129, v180, s[96:97]
	s_lshl_b32 s21, s56, 11
	s_add_u32 s21, s21, 0x2c440400
	v_add_u32_e32 v129, s21, v161
	global_store_dword v129, v175, s[96:97]
	s_lshl_b32 s21, s56, 11
	s_add_u32 s21, s21, 0x2e440400
	v_add_u32_e32 v129, s21, v161
	global_store_dword v129, v179, s[96:97]
	s_lshl_b32 s21, s56, 11
	s_add_u32 s21, s21, 0x30440400
	v_add_u32_e32 v129, s21, v161
	global_store_dword v129, v181, s[96:97]
	v_mul_f32_e32 v182, v188, v178
	v_mul_f32_e32 v183, v188, v179
	v_mul_f32_e32 v154, v141, v182
	v_fmac_f32_e32 v154, v141, v183
	s_lshl_b32 s21, s56, 11
	s_add_u32 s21, s21, 0x28440400
	v_add_u32_e32 v129, s21, v161
	global_store_dword v129, v188, s[96:97]
	s_lshl_b32 s21, s56, 11
	s_add_u32 s21, s21, 0x29440400
	v_add_u32_e32 v129, s21, v161
	global_store_dword v129, v226, s[96:97]
	s_lshl_b32 s21, s56, 11
	s_add_u32 s21, s21, 0x2a440400
	v_add_u32_e32 v129, s21, v161
	global_store_dword v129, v146, s[96:97]
	v_add_f32_e32 v174, v142, v116
	v_add_f32_e32 v176, v144, v114
	v_add_f32_e32 v175, v143, v110
	v_add_f32_e32 v177, v145, v112
	v_mul_f32_e32 v174, 0xbfb8aa3b, v174
	v_mul_f32_e32 v175, 0xbfb8aa3b, v175
	v_mul_f32_e32 v176, 0xbfb8aa3b, v176
	v_mul_f32_e32 v177, 0xbfb8aa3b, v177
	v_exp_f32_e32 v174, v174
	v_exp_f32_e32 v175, v175
	v_exp_f32_e32 v176, v176
	v_exp_f32_e32 v177, v177
	s_nop 0
	v_add_f32_e32 v174, 1.0, v174
	v_add_f32_e32 v175, 1.0, v175
	v_add_f32_e32 v176, 1.0, v176
	v_add_f32_e32 v177, 1.0, v177
	v_rcp_f32_e32 v174, v174
	v_rcp_f32_e32 v175, v175
	v_rcp_f32_e32 v176, v176
	v_rcp_f32_e32 v177, v177
	s_nop 0
	v_mul_f32_e32 v174, 0xbf1b4598, v174
	v_mul_f32_e32 v175, 0xbf1b4598, v175
	v_mul_f32_e32 v174, 0x3fb8aa3b, v174
	v_mul_f32_e32 v175, 0x3fb8aa3b, v175
	v_exp_f32_e32 v174, v174
	v_exp_f32_e32 v175, v175
	v_add_f32_e32 v178, -1.0, v176
	v_add_f32_e32 v179, -1.0, v177
	v_fma_f32 v178, v140, v178, 1.0
	v_fma_f32 v179, v140, v179, 1.0
	v_mul_f32_e32 v178, v178, v219
	v_mul_f32_e32 v180, v147, v176
	v_mul_f32_e32 v179, v179, v219
	v_mul_f32_e32 v181, v147, v177
	s_lshl_b32 s21, s56, 11
	s_add_u32 s21, s21, 0x2b440c00
	v_add_u32_e32 v129, s21, v161
	global_store_dword v129, v174, s[96:97]
	s_lshl_b32 s21, s56, 11
	s_add_u32 s21, s21, 0x2d440c00
	v_add_u32_e32 v129, s21, v161
	global_store_dword v129, v178, s[96:97]
	s_lshl_b32 s21, s56, 11
	s_add_u32 s21, s21, 0x2f440c00
	v_add_u32_e32 v129, s21, v161
	global_store_dword v129, v180, s[96:97]
; template <bool RWONLY>
; __device__ __forceinline__ void phase_prep(const Params p, int l, char* smem) {
;     ...
; #pragma unroll
;           for (int n = 0; n < 2; ++n) {
;             float zw = (n ? w0c1 : w0c0) + acc[tk][n][ch];
;             float za = (n ? a0c1 : a0c0) + acc[tk][2 + n][ch];
;             float dec = __expf(-0.6065306597126334f * sigmoidf_(zw));
;             float a = sigmoidf_(za);
;             float kd = k * (1.f + (a - 1.f) * kac);
;             float bb = kk * a;
;             size_t o = ((size_t)n * S_ + s) * 512 + c;
;             ((float*)(ws + OFF_SCW))[o] = dec;
;             ((float*)(ws + OFF_SCKD))[o] = kd;
;             ((float*)(ws + OFF_SCB))[o] = bb;
;             bsum += r * kd * rkc;
;           }
;           size_t o1 = (size_t)s * 512 + c;
;           ((float*)(ws + OFF_SCR))[o1] = r;
;           ((float*)(ws + OFF_SCV))[o1] = v;
;           ((float*)(ws + OFF_SCKK))[o1] = kk;
	s_lshl_b32 s21, s56, 11
	s_add_u32 s21, s21, 0x2c440c00
	v_add_u32_e32 v129, s21, v161
	global_store_dword v129, v175, s[96:97]
	s_lshl_b32 s21, s56, 11
	s_add_u32 s21, s21, 0x2e440c00
	v_add_u32_e32 v129, s21, v161
	global_store_dword v129, v179, s[96:97]
	s_lshl_b32 s21, s56, 11
	s_add_u32 s21, s21, 0x30440c00
	v_add_u32_e32 v129, s21, v161
	global_store_dword v129, v181, s[96:97]
	v_mul_f32_e32 v182, v189, v178
	v_mul_f32_e32 v183, v189, v179
	v_mul_f32_e32 v155, v141, v182
	v_fmac_f32_e32 v155, v141, v183
	s_lshl_b32 s21, s56, 11
	s_add_u32 s21, s21, 0x28440c00
	v_add_u32_e32 v129, s21, v161
	global_store_dword v129, v189, s[96:97]
	s_lshl_b32 s21, s56, 11
	s_add_u32 s21, s21, 0x29440c00
	v_add_u32_e32 v129, s21, v161
	global_store_dword v129, v227, s[96:97]
	s_lshl_b32 s21, s56, 11
	s_add_u32 s21, s21, 0x2a440c00
	v_add_u32_e32 v129, s21, v161
	global_store_dword v129, v147, s[96:97]
	v_add_f32_e32 v174, v142, v108
	v_add_f32_e32 v176, v144, v106
	v_add_f32_e32 v175, v143, v102
	v_add_f32_e32 v177, v145, v104
	v_mul_f32_e32 v174, 0xbfb8aa3b, v174
	v_mul_f32_e32 v175, 0xbfb8aa3b, v175
	v_mul_f32_e32 v176, 0xbfb8aa3b, v176
	v_mul_f32_e32 v177, 0xbfb8aa3b, v177
	v_exp_f32_e32 v174, v174
	v_exp_f32_e32 v175, v175
	v_exp_f32_e32 v176, v176
	v_exp_f32_e32 v177, v177
	s_nop 0
	v_add_f32_e32 v174, 1.0, v174
	v_add_f32_e32 v175, 1.0, v175
	v_add_f32_e32 v176, 1.0, v176
	v_add_f32_e32 v177, 1.0, v177
	v_rcp_f32_e32 v174, v174
	v_rcp_f32_e32 v175, v175
	v_rcp_f32_e32 v176, v176
	v_rcp_f32_e32 v177, v177
	s_nop 0
	v_mul_f32_e32 v174, 0xbf1b4598, v174
	v_mul_f32_e32 v175, 0xbf1b4598, v175
	v_mul_f32_e32 v174, 0x3fb8aa3b, v174
	v_mul_f32_e32 v175, 0x3fb8aa3b, v175
	v_exp_f32_e32 v174, v174
	v_exp_f32_e32 v175, v175
	v_add_f32_e32 v178, -1.0, v176
	v_add_f32_e32 v179, -1.0, v177
	v_fma_f32 v178, v140, v178, 1.0
	v_fma_f32 v179, v140, v179, 1.0
	v_mul_f32_e32 v178, v178, v220
	v_mul_f32_e32 v180, v148, v176
	v_mul_f32_e32 v179, v179, v220
	v_mul_f32_e32 v181, v148, v177
	s_lshl_b32 s21, s56, 11
	s_add_u32 s21, s21, 0x2b441400
	v_add_u32_e32 v129, s21, v161
	global_store_dword v129, v174, s[96:97]
	s_lshl_b32 s21, s56, 11
	s_add_u32 s21, s21, 0x2d441400
	v_add_u32_e32 v129, s21, v161
	global_store_dword v129, v178, s[96:97]
	s_lshl_b32 s21, s56, 11
	s_add_u32 s21, s21, 0x2f441400
	v_add_u32_e32 v129, s21, v161
	global_store_dword v129, v180, s[96:97]
	s_lshl_b32 s21, s56, 11
	s_add_u32 s21, s21, 0x2c441400
	v_add_u32_e32 v129, s21, v161
	global_store_dword v129, v175, s[96:97]
	s_lshl_b32 s21, s56, 11
	s_add_u32 s21, s21, 0x2e441400
	v_add_u32_e32 v129, s21, v161
	global_store_dword v129, v179, s[96:97]
	s_lshl_b32 s21, s56, 11
	s_add_u32 s21, s21, 0x30441400
	v_add_u32_e32 v129, s21, v161
	global_store_dword v129, v181, s[96:97]
	v_mul_f32_e32 v182, v190, v178
	v_mul_f32_e32 v183, v190, v179
	v_mul_f32_e32 v156, v141, v182
	v_fmac_f32_e32 v156, v141, v183
	s_lshl_b32 s21, s56, 11
	s_add_u32 s21, s21, 0x28441400
	v_add_u32_e32 v129, s21, v161
	global_store_dword v129, v190, s[96:97]
	s_lshl_b32 s21, s56, 11
	s_add_u32 s21, s21, 0x29441400
	v_add_u32_e32 v129, s21, v161
	global_store_dword v129, v228, s[96:97]
	s_lshl_b32 s21, s56, 11
	s_add_u32 s21, s21, 0x2a441400
	v_add_u32_e32 v129, s21, v161
	global_store_dword v129, v148, s[96:97]
	v_add_f32_e32 v174, v142, v100
	v_add_f32_e32 v176, v144, v98
	v_add_f32_e32 v175, v143, v96
	v_add_f32_e32 v177, v145, v94
	v_mul_f32_e32 v174, 0xbfb8aa3b, v174
	v_mul_f32_e32 v175, 0xbfb8aa3b, v175
	v_mul_f32_e32 v176, 0xbfb8aa3b, v176
	v_mul_f32_e32 v177, 0xbfb8aa3b, v177
	v_exp_f32_e32 v174, v174
	v_exp_f32_e32 v175, v175
	v_exp_f32_e32 v176, v176
	v_exp_f32_e32 v177, v177
	s_nop 0
	v_add_f32_e32 v174, 1.0, v174
	v_add_f32_e32 v175, 1.0, v175
	v_add_f32_e32 v176, 1.0, v176
	v_add_f32_e32 v177, 1.0, v177
	v_rcp_f32_e32 v174, v174
	v_rcp_f32_e32 v175, v175
	v_rcp_f32_e32 v176, v176
	v_rcp_f32_e32 v177, v177
	s_nop 0
	v_mul_f32_e32 v174, 0xbf1b4598, v174
	v_mul_f32_e32 v175, 0xbf1b4598, v175
	v_mul_f32_e32 v174, 0x3fb8aa3b, v174
	v_mul_f32_e32 v175, 0x3fb8aa3b, v175
	v_exp_f32_e32 v174, v174
	v_exp_f32_e32 v175, v175
	v_add_f32_e32 v178, -1.0, v176
	v_add_f32_e32 v179, -1.0, v177
	v_fma_f32 v178, v140, v178, 1.0
	v_fma_f32 v179, v140, v179, 1.0
	v_mul_f32_e32 v178, v178, v221
	v_mul_f32_e32 v180, v149, v176
	v_mul_f32_e32 v179, v179, v221
	v_mul_f32_e32 v181, v149, v177
	s_lshl_b32 s21, s56, 11
	s_add_u32 s21, s21, 0x2b441c00
	v_add_u32_e32 v129, s21, v161
	global_store_dword v129, v174, s[96:97]
	s_lshl_b32 s21, s56, 11
	s_add_u32 s21, s21, 0x2d441c00
	v_add_u32_e32 v129, s21, v161
	global_store_dword v129, v178, s[96:97]
	s_lshl_b32 s21, s56, 11
	s_add_u32 s21, s21, 0x2f441c00
	v_add_u32_e32 v129, s21, v161
	global_store_dword v129, v180, s[96:97]
	s_lshl_b32 s21, s56, 11
	s_add_u32 s21, s21, 0x2c441c00
	v_add_u32_e32 v129, s21, v161
	global_store_dword v129, v175, s[96:97]
	s_lshl_b32 s21, s56, 11
	s_add_u32 s21, s21, 0x2e441c00
	v_add_u32_e32 v129, s21, v161
	global_store_dword v129, v179, s[96:97]
	s_lshl_b32 s21, s56, 11
	s_add_u32 s21, s21, 0x30441c00
	v_add_u32_e32 v129, s21, v161
	global_store_dword v129, v181, s[96:97]
	v_mul_f32_e32 v182, v191, v178
	v_mul_f32_e32 v183, v191, v179
	v_mul_f32_e32 v157, v141, v182
	v_fmac_f32_e32 v157, v141, v183
	s_lshl_b32 s21, s56, 11
	s_add_u32 s21, s21, 0x28441c00
	v_add_u32_e32 v129, s21, v161
	global_store_dword v129, v191, s[96:97]
	s_lshl_b32 s21, s56, 11
	s_add_u32 s21, s21, 0x29441c00
	v_add_u32_e32 v129, s21, v161
	global_store_dword v129, v229, s[96:97]
	s_lshl_b32 s21, s56, 11
	s_add_u32 s21, s21, 0x2a441c00
	v_add_u32_e32 v129, s21, v161
; template <bool RWONLY>
; __device__ __forceinline__ void phase_prep(const Params p, int l, char* smem) {
;     ...
; #pragma unroll
;           for (int n = 0; n < 2; ++n) {
;             float zw = (n ? w0c1 : w0c0) + acc[tk][n][ch];
;             float za = (n ? a0c1 : a0c0) + acc[tk][2 + n][ch];
;             float dec = __expf(-0.6065306597126334f * sigmoidf_(zw));
;             float a = sigmoidf_(za);
;             float kd = k * (1.f + (a - 1.f) * kac);
;             float bb = kk * a;
;             size_t o = ((size_t)n * S_ + s) * 512 + c;
;             ((float*)(ws + OFF_SCW))[o] = dec;
;             ((float*)(ws + OFF_SCKD))[o] = kd;
;             ((float*)(ws + OFF_SCB))[o] = bb;
;             bsum += r * kd * rkc;
;           }
;           size_t o1 = (size_t)s * 512 + c;
;           ((float*)(ws + OFF_SCR))[o1] = r;
;           ((float*)(ws + OFF_SCV))[o1] = v;
;           ((float*)(ws + OFF_SCKK))[o1] = kk;
	global_store_dword v129, v149, s[96:97]
	v_add_f32_e32 v174, v142, v91
	v_add_f32_e32 v176, v144, v93
	v_add_f32_e32 v175, v143, v87
	v_add_f32_e32 v177, v145, v89
	v_mul_f32_e32 v174, 0xbfb8aa3b, v174
	v_mul_f32_e32 v175, 0xbfb8aa3b, v175
	v_mul_f32_e32 v176, 0xbfb8aa3b, v176
	v_mul_f32_e32 v177, 0xbfb8aa3b, v177
	v_exp_f32_e32 v174, v174
	v_exp_f32_e32 v175, v175
	v_exp_f32_e32 v176, v176
	v_exp_f32_e32 v177, v177
	s_nop 0
	v_add_f32_e32 v174, 1.0, v174
	v_add_f32_e32 v175, 1.0, v175
	v_add_f32_e32 v176, 1.0, v176
	v_add_f32_e32 v177, 1.0, v177
	v_rcp_f32_e32 v174, v174
	v_rcp_f32_e32 v175, v175
	v_rcp_f32_e32 v176, v176
	v_rcp_f32_e32 v177, v177
	s_nop 0
	v_mul_f32_e32 v174, 0xbf1b4598, v174
	v_mul_f32_e32 v175, 0xbf1b4598, v175
	v_mul_f32_e32 v174, 0x3fb8aa3b, v174
	v_mul_f32_e32 v175, 0x3fb8aa3b, v175
	v_exp_f32_e32 v174, v174
	v_exp_f32_e32 v175, v175
	v_add_f32_e32 v178, -1.0, v176
	v_add_f32_e32 v179, -1.0, v177
	v_fma_f32 v178, v140, v178, 1.0
	v_fma_f32 v179, v140, v179, 1.0
	v_mul_f32_e32 v178, v178, v222
	v_mul_f32_e32 v180, v150, v176
	v_mul_f32_e32 v179, v179, v222
	v_mul_f32_e32 v181, v150, v177
	s_lshl_b32 s21, s56, 11
	s_add_u32 s21, s21, 0x2b442400
	v_add_u32_e32 v129, s21, v161
	global_store_dword v129, v174, s[96:97]
	s_lshl_b32 s21, s56, 11
	s_add_u32 s21, s21, 0x2d442400
	v_add_u32_e32 v129, s21, v161
	global_store_dword v129, v178, s[96:97]
	s_lshl_b32 s21, s56, 11
	s_add_u32 s21, s21, 0x2f442400
	v_add_u32_e32 v129, s21, v161
	global_store_dword v129, v180, s[96:97]
	s_lshl_b32 s21, s56, 11
	s_add_u32 s21, s21, 0x2c442400
	v_add_u32_e32 v129, s21, v161
	global_store_dword v129, v175, s[96:97]
	s_lshl_b32 s21, s56, 11
	s_add_u32 s21, s21, 0x2e442400
	v_add_u32_e32 v129, s21, v161
	global_store_dword v129, v179, s[96:97]
	s_lshl_b32 s21, s56, 11
	s_add_u32 s21, s21, 0x30442400
	v_add_u32_e32 v129, s21, v161
	global_store_dword v129, v181, s[96:97]
	v_mul_f32_e32 v182, v214, v178
	v_mul_f32_e32 v183, v214, v179
	v_mul_f32_e32 v158, v141, v182
	v_fmac_f32_e32 v158, v141, v183
	s_lshl_b32 s21, s56, 11
	s_add_u32 s21, s21, 0x28442400
	v_add_u32_e32 v129, s21, v161
	global_store_dword v129, v214, s[96:97]
	s_lshl_b32 s21, s56, 11
	s_add_u32 s21, s21, 0x29442400
	v_add_u32_e32 v129, s21, v161
	global_store_dword v129, v230, s[96:97]
	s_lshl_b32 s21, s56, 11
	s_add_u32 s21, s21, 0x2a442400
	v_add_u32_e32 v129, s21, v161
	global_store_dword v129, v150, s[96:97]
	v_add_f32_e32 v174, v142, v83
	v_add_f32_e32 v176, v144, v85
	v_add_f32_e32 v175, v143, v79
	v_add_f32_e32 v177, v145, v81
	v_mul_f32_e32 v174, 0xbfb8aa3b, v174
	v_mul_f32_e32 v175, 0xbfb8aa3b, v175
	v_mul_f32_e32 v176, 0xbfb8aa3b, v176
	v_mul_f32_e32 v177, 0xbfb8aa3b, v177
	v_exp_f32_e32 v174, v174
	v_exp_f32_e32 v175, v175
	v_exp_f32_e32 v176, v176
	v_exp_f32_e32 v177, v177
	s_nop 0
	v_add_f32_e32 v174, 1.0, v174
	v_add_f32_e32 v175, 1.0, v175
	v_add_f32_e32 v176, 1.0, v176
	v_add_f32_e32 v177, 1.0, v177
	v_rcp_f32_e32 v174, v174
	v_rcp_f32_e32 v175, v175
	v_rcp_f32_e32 v176, v176
	v_rcp_f32_e32 v177, v177
	s_nop 0
	v_mul_f32_e32 v174, 0xbf1b4598, v174
	v_mul_f32_e32 v175, 0xbf1b4598, v175
	v_mul_f32_e32 v174, 0x3fb8aa3b, v174
	v_mul_f32_e32 v175, 0x3fb8aa3b, v175
	v_exp_f32_e32 v174, v174
	v_exp_f32_e32 v175, v175
	v_add_f32_e32 v178, -1.0, v176
	v_add_f32_e32 v179, -1.0, v177
	v_fma_f32 v178, v140, v178, 1.0
	v_fma_f32 v179, v140, v179, 1.0
	v_mul_f32_e32 v178, v178, v223
	v_mul_f32_e32 v180, v151, v176
	v_mul_f32_e32 v179, v179, v223
	v_mul_f32_e32 v181, v151, v177
	s_lshl_b32 s21, s56, 11
	s_add_u32 s21, s21, 0x2b442c00
	v_add_u32_e32 v129, s21, v161
	global_store_dword v129, v174, s[96:97]
	s_lshl_b32 s21, s56, 11
	s_add_u32 s21, s21, 0x2d442c00
	v_add_u32_e32 v129, s21, v161
	global_store_dword v129, v178, s[96:97]
	s_lshl_b32 s21, s56, 11
	s_add_u32 s21, s21, 0x2f442c00
	v_add_u32_e32 v129, s21, v161
	global_store_dword v129, v180, s[96:97]
	s_lshl_b32 s21, s56, 11
	s_add_u32 s21, s21, 0x2c442c00
	v_add_u32_e32 v129, s21, v161
	global_store_dword v129, v175, s[96:97]
	s_lshl_b32 s21, s56, 11
	s_add_u32 s21, s21, 0x2e442c00
	v_add_u32_e32 v129, s21, v161
	global_store_dword v129, v179, s[96:97]
	s_lshl_b32 s21, s56, 11
	s_add_u32 s21, s21, 0x30442c00
	v_add_u32_e32 v129, s21, v161
	global_store_dword v129, v181, s[96:97]
	v_mul_f32_e32 v182, v215, v178
	v_mul_f32_e32 v183, v215, v179
	v_mul_f32_e32 v159, v141, v182
	v_fmac_f32_e32 v159, v141, v183
	s_lshl_b32 s21, s56, 11
	s_add_u32 s21, s21, 0x28442c00
	v_add_u32_e32 v129, s21, v161
	global_store_dword v129, v215, s[96:97]
	s_lshl_b32 s21, s56, 11
	s_add_u32 s21, s21, 0x29442c00
	v_add_u32_e32 v129, s21, v161
	global_store_dword v129, v231, s[96:97]
	s_lshl_b32 s21, s56, 11
	s_add_u32 s21, s21, 0x2a442c00
	v_add_u32_e32 v129, s21, v161
	global_store_dword v129, v151, s[96:97]
	v_add_f32_e32 v174, v142, v75
	v_add_f32_e32 v176, v144, v77
	v_add_f32_e32 v175, v143, v71
	v_add_f32_e32 v177, v145, v73
	v_mul_f32_e32 v174, 0xbfb8aa3b, v174
	v_mul_f32_e32 v175, 0xbfb8aa3b, v175
	v_mul_f32_e32 v176, 0xbfb8aa3b, v176
	v_mul_f32_e32 v177, 0xbfb8aa3b, v177
	v_exp_f32_e32 v174, v174
	v_exp_f32_e32 v175, v175
	v_exp_f32_e32 v176, v176
	v_exp_f32_e32 v177, v177
	s_nop 0
	v_add_f32_e32 v174, 1.0, v174
	v_add_f32_e32 v175, 1.0, v175
	v_add_f32_e32 v176, 1.0, v176
	v_add_f32_e32 v177, 1.0, v177
	v_rcp_f32_e32 v174, v174
	v_rcp_f32_e32 v175, v175
	v_rcp_f32_e32 v176, v176
	v_rcp_f32_e32 v177, v177
	s_nop 0
	v_mul_f32_e32 v174, 0xbf1b4598, v174
	v_mul_f32_e32 v175, 0xbf1b4598, v175
	v_mul_f32_e32 v174, 0x3fb8aa3b, v174
	v_mul_f32_e32 v175, 0x3fb8aa3b, v175
	v_exp_f32_e32 v174, v174
	v_exp_f32_e32 v175, v175
; template <bool RWONLY>
; __device__ __forceinline__ void phase_prep(const Params p, int l, char* smem) {
;     ...
; #pragma unroll
;           for (int n = 0; n < 2; ++n) {
;             float zw = (n ? w0c1 : w0c0) + acc[tk][n][ch];
;             float za = (n ? a0c1 : a0c0) + acc[tk][2 + n][ch];
;             float dec = __expf(-0.6065306597126334f * sigmoidf_(zw));
;             float a = sigmoidf_(za);
;             float kd = k * (1.f + (a - 1.f) * kac);
;             float bb = kk * a;
;             size_t o = ((size_t)n * S_ + s) * 512 + c;
;             ((float*)(ws + OFF_SCW))[o] = dec;
;             ((float*)(ws + OFF_SCKD))[o] = kd;
;             ((float*)(ws + OFF_SCB))[o] = bb;
;             bsum += r * kd * rkc;
;           }
;           size_t o1 = (size_t)s * 512 + c;
;           ((float*)(ws + OFF_SCR))[o1] = r;
;           ((float*)(ws + OFF_SCV))[o1] = v;
;           ((float*)(ws + OFF_SCKK))[o1] = kk;
;           float bon = wave_sum(bsum);
	v_add_f32_e32 v178, -1.0, v176
	v_add_f32_e32 v179, -1.0, v177
	v_fma_f32 v178, v140, v178, 1.0
	v_fma_f32 v179, v140, v179, 1.0
	v_mul_f32_e32 v178, v178, v224
	v_mul_f32_e32 v180, v152, v176
	v_mul_f32_e32 v179, v179, v224
	v_mul_f32_e32 v181, v152, v177
	s_lshl_b32 s21, s56, 11
	s_add_u32 s21, s21, 0x2b443400
	v_add_u32_e32 v129, s21, v161
	global_store_dword v129, v174, s[96:97]
	s_lshl_b32 s21, s56, 11
	s_add_u32 s21, s21, 0x2d443400
	v_add_u32_e32 v129, s21, v161
	global_store_dword v129, v178, s[96:97]
	s_lshl_b32 s21, s56, 11
	s_add_u32 s21, s21, 0x2f443400
	v_add_u32_e32 v129, s21, v161
	global_store_dword v129, v180, s[96:97]
	s_lshl_b32 s21, s56, 11
	s_add_u32 s21, s21, 0x2c443400
	v_add_u32_e32 v129, s21, v161
	global_store_dword v129, v175, s[96:97]
	s_lshl_b32 s21, s56, 11
	s_add_u32 s21, s21, 0x2e443400
	v_add_u32_e32 v129, s21, v161
	global_store_dword v129, v179, s[96:97]
	s_lshl_b32 s21, s56, 11
	s_add_u32 s21, s21, 0x30443400
	v_add_u32_e32 v129, s21, v161
	global_store_dword v129, v181, s[96:97]
	v_mul_f32_e32 v182, v216, v178
	v_mul_f32_e32 v183, v216, v179
	v_mul_f32_e32 v172, v141, v182
	v_fmac_f32_e32 v172, v141, v183
	s_lshl_b32 s21, s56, 11
	s_add_u32 s21, s21, 0x28443400
	v_add_u32_e32 v129, s21, v161
	global_store_dword v129, v216, s[96:97]
	s_lshl_b32 s21, s56, 11
	s_add_u32 s21, s21, 0x29443400
	v_add_u32_e32 v129, s21, v161
	global_store_dword v129, v232, s[96:97]
	s_lshl_b32 s21, s56, 11
	s_add_u32 s21, s21, 0x2a443400
	v_add_u32_e32 v129, s21, v161
	global_store_dword v129, v152, s[96:97]
	v_add_f32_e32 v174, v142, v67
	v_add_f32_e32 v176, v144, v69
	v_add_f32_e32 v175, v143, v63
	v_add_f32_e32 v177, v145, v65
	v_mul_f32_e32 v174, 0xbfb8aa3b, v174
	v_mul_f32_e32 v175, 0xbfb8aa3b, v175
	v_mul_f32_e32 v176, 0xbfb8aa3b, v176
	v_mul_f32_e32 v177, 0xbfb8aa3b, v177
	v_exp_f32_e32 v174, v174
	v_exp_f32_e32 v175, v175
	v_exp_f32_e32 v176, v176
	v_exp_f32_e32 v177, v177
	s_nop 0
	v_add_f32_e32 v174, 1.0, v174
	v_add_f32_e32 v175, 1.0, v175
	v_add_f32_e32 v176, 1.0, v176
	v_add_f32_e32 v177, 1.0, v177
	v_rcp_f32_e32 v174, v174
	v_rcp_f32_e32 v175, v175
	v_rcp_f32_e32 v176, v176
	v_rcp_f32_e32 v177, v177
	s_nop 0
	v_mul_f32_e32 v174, 0xbf1b4598, v174
	v_mul_f32_e32 v175, 0xbf1b4598, v175
	v_mul_f32_e32 v174, 0x3fb8aa3b, v174
	v_mul_f32_e32 v175, 0x3fb8aa3b, v175
	v_exp_f32_e32 v174, v174
	v_exp_f32_e32 v175, v175
	v_add_f32_e32 v178, -1.0, v176
	v_add_f32_e32 v179, -1.0, v177
	v_fma_f32 v178, v140, v178, 1.0
	v_fma_f32 v179, v140, v179, 1.0
	v_mul_f32_e32 v178, v178, v225
	v_mul_f32_e32 v180, v153, v176
	v_mul_f32_e32 v179, v179, v225
	v_mul_f32_e32 v181, v153, v177
	s_lshl_b32 s21, s56, 11
	s_add_u32 s21, s21, 0x2b443c00
	v_add_u32_e32 v129, s21, v161
	global_store_dword v129, v174, s[96:97]
	s_lshl_b32 s21, s56, 11
	s_add_u32 s21, s21, 0x2d443c00
	v_add_u32_e32 v129, s21, v161
	global_store_dword v129, v178, s[96:97]
	s_lshl_b32 s21, s56, 11
	s_add_u32 s21, s21, 0x2f443c00
	v_add_u32_e32 v129, s21, v161
	global_store_dword v129, v180, s[96:97]
	s_lshl_b32 s21, s56, 11
	s_add_u32 s21, s21, 0x2c443c00
	v_add_u32_e32 v129, s21, v161
	global_store_dword v129, v175, s[96:97]
	s_lshl_b32 s21, s56, 11
	s_add_u32 s21, s21, 0x2e443c00
	v_add_u32_e32 v129, s21, v161
	global_store_dword v129, v179, s[96:97]
	s_lshl_b32 s21, s56, 11
	s_add_u32 s21, s21, 0x30443c00
	v_add_u32_e32 v129, s21, v161
	global_store_dword v129, v181, s[96:97]
	v_mul_f32_e32 v182, v217, v178
	v_mul_f32_e32 v183, v217, v179
	v_mul_f32_e32 v173, v141, v182
	v_fmac_f32_e32 v173, v141, v183
	s_lshl_b32 s21, s56, 11
	s_add_u32 s21, s21, 0x28443c00
	v_add_u32_e32 v129, s21, v161
	global_store_dword v129, v217, s[96:97]
	s_lshl_b32 s21, s56, 11
	s_add_u32 s21, s21, 0x29443c00
	v_add_u32_e32 v129, s21, v161
	global_store_dword v129, v233, s[96:97]
	s_lshl_b32 s21, s56, 11
	s_add_u32 s21, s21, 0x2a443c00
	v_add_u32_e32 v129, s21, v161
	global_store_dword v129, v153, s[96:97]
	v_add_f32_dpp v154, v154, v154 quad_perm:[1,0,3,2] row_mask:0xf bank_mask:0xf bound_ctrl:1
	v_add_f32_dpp v155, v155, v155 quad_perm:[1,0,3,2] row_mask:0xf bank_mask:0xf bound_ctrl:1
	v_add_f32_dpp v156, v156, v156 quad_perm:[1,0,3,2] row_mask:0xf bank_mask:0xf bound_ctrl:1
	v_add_f32_dpp v157, v157, v157 quad_perm:[1,0,3,2] row_mask:0xf bank_mask:0xf bound_ctrl:1
	v_add_f32_dpp v158, v158, v158 quad_perm:[1,0,3,2] row_mask:0xf bank_mask:0xf bound_ctrl:1
	v_add_f32_dpp v159, v159, v159 quad_perm:[1,0,3,2] row_mask:0xf bank_mask:0xf bound_ctrl:1
	v_add_f32_dpp v172, v172, v172 quad_perm:[1,0,3,2] row_mask:0xf bank_mask:0xf bound_ctrl:1
	v_add_f32_dpp v173, v173, v173 quad_perm:[1,0,3,2] row_mask:0xf bank_mask:0xf bound_ctrl:1
; template <bool RWONLY>
; __device__ __forceinline__ void phase_prep(const Params p, int l, char* smem) {
;     ...
;           float bon = wave_sum(bsum);
;           if (lane == 0) ((float*)(ws + OFF_BONUS))[s * 8 + w + 4 * ch] = bon;
	v_add_f32_dpp v154, v154, v154 quad_perm:[2,3,0,1] row_mask:0xf bank_mask:0xf bound_ctrl:1
	v_add_f32_dpp v155, v155, v155 quad_perm:[2,3,0,1] row_mask:0xf bank_mask:0xf bound_ctrl:1
	v_add_f32_dpp v156, v156, v156 quad_perm:[2,3,0,1] row_mask:0xf bank_mask:0xf bound_ctrl:1
	v_add_f32_dpp v157, v157, v157 quad_perm:[2,3,0,1] row_mask:0xf bank_mask:0xf bound_ctrl:1
	v_add_f32_dpp v158, v158, v158 quad_perm:[2,3,0,1] row_mask:0xf bank_mask:0xf bound_ctrl:1
	v_add_f32_dpp v159, v159, v159 quad_perm:[2,3,0,1] row_mask:0xf bank_mask:0xf bound_ctrl:1
	v_add_f32_dpp v172, v172, v172 quad_perm:[2,3,0,1] row_mask:0xf bank_mask:0xf bound_ctrl:1
	v_add_f32_dpp v173, v173, v173 quad_perm:[2,3,0,1] row_mask:0xf bank_mask:0xf bound_ctrl:1
	v_add_f32_dpp v154, v154, v154 row_half_mirror row_mask:0xf bank_mask:0xf bound_ctrl:1
	v_add_f32_dpp v155, v155, v155 row_half_mirror row_mask:0xf bank_mask:0xf bound_ctrl:1
	v_add_f32_dpp v156, v156, v156 row_half_mirror row_mask:0xf bank_mask:0xf bound_ctrl:1
	v_add_f32_dpp v157, v157, v157 row_half_mirror row_mask:0xf bank_mask:0xf bound_ctrl:1
	v_add_f32_dpp v158, v158, v158 row_half_mirror row_mask:0xf bank_mask:0xf bound_ctrl:1
	v_add_f32_dpp v159, v159, v159 row_half_mirror row_mask:0xf bank_mask:0xf bound_ctrl:1
	v_add_f32_dpp v172, v172, v172 row_half_mirror row_mask:0xf bank_mask:0xf bound_ctrl:1
	v_add_f32_dpp v173, v173, v173 row_half_mirror row_mask:0xf bank_mask:0xf bound_ctrl:1
	v_add_f32_dpp v154, v154, v154 row_mirror row_mask:0xf bank_mask:0xf bound_ctrl:1
	v_add_f32_dpp v155, v155, v155 row_mirror row_mask:0xf bank_mask:0xf bound_ctrl:1
	v_add_f32_dpp v156, v156, v156 row_mirror row_mask:0xf bank_mask:0xf bound_ctrl:1
	v_add_f32_dpp v157, v157, v157 row_mirror row_mask:0xf bank_mask:0xf bound_ctrl:1
	v_add_f32_dpp v158, v158, v158 row_mirror row_mask:0xf bank_mask:0xf bound_ctrl:1
	v_add_f32_dpp v159, v159, v159 row_mirror row_mask:0xf bank_mask:0xf bound_ctrl:1
	v_add_f32_dpp v172, v172, v172 row_mirror row_mask:0xf bank_mask:0xf bound_ctrl:1
	v_add_f32_dpp v173, v173, v173 row_mirror row_mask:0xf bank_mask:0xf bound_ctrl:1
	ds_bpermute_b32 v174, v163, v154
	ds_bpermute_b32 v175, v163, v155
	ds_bpermute_b32 v176, v163, v156
	ds_bpermute_b32 v177, v163, v157
	ds_bpermute_b32 v178, v163, v158
	ds_bpermute_b32 v179, v163, v159
	ds_bpermute_b32 v180, v163, v172
	ds_bpermute_b32 v181, v163, v173
	s_waitcnt lgkmcnt(0)
	v_add_f32_e32 v154, v154, v174
	v_add_f32_e32 v155, v155, v175
	v_add_f32_e32 v156, v156, v176
	v_add_f32_e32 v157, v157, v177
	v_add_f32_e32 v158, v158, v178
	v_add_f32_e32 v159, v159, v179
	v_add_f32_e32 v172, v172, v180
	v_add_f32_e32 v173, v173, v181
	ds_bpermute_b32 v174, v162, v154
	ds_bpermute_b32 v175, v162, v155
	ds_bpermute_b32 v176, v162, v156
	ds_bpermute_b32 v177, v162, v157
	ds_bpermute_b32 v178, v162, v158
	ds_bpermute_b32 v179, v162, v159
	ds_bpermute_b32 v180, v162, v172
	ds_bpermute_b32 v181, v162, v173
	s_waitcnt lgkmcnt(0)
	v_add_f32_e32 v154, v154, v174
	v_add_f32_e32 v155, v155, v175
	v_add_f32_e32 v156, v156, v176
	v_add_f32_e32 v157, v157, v177
	v_add_f32_e32 v158, v158, v178
	v_add_f32_e32 v159, v159, v179
	v_add_f32_e32 v172, v172, v180
	v_add_f32_e32 v173, v173, v181
	s_and_saveexec_b64 s[2:3], s[40:41]
	s_lshl_b32 s21, s56, 5
	s_add_u32 s21, s21, 0x31440010
	v_add_u32_e32 v129, s21, v126
	global_store_dword v129, v154, s[96:97]
	s_lshl_b32 s21, s56, 5
	s_add_u32 s21, s21, 0x31440030
	v_add_u32_e32 v129, s21, v126
	global_store_dword v129, v155, s[96:97]
	s_lshl_b32 s21, s56, 5
	s_add_u32 s21, s21, 0x31440050
	v_add_u32_e32 v129, s21, v126
	global_store_dword v129, v156, s[96:97]
	s_lshl_b32 s21, s56, 5
	s_add_u32 s21, s21, 0x31440070
	v_add_u32_e32 v129, s21, v126
	global_store_dword v129, v157, s[96:97]
	s_lshl_b32 s21, s56, 5
	s_add_u32 s21, s21, 0x31440090
	v_add_u32_e32 v129, s21, v126
	global_store_dword v129, v158, s[96:97]
	s_lshl_b32 s21, s56, 5
	s_add_u32 s21, s21, 0x314400b0
	v_add_u32_e32 v129, s21, v126
	global_store_dword v129, v159, s[96:97]
	s_lshl_b32 s21, s56, 5
	s_add_u32 s21, s21, 0x314400d0
	v_add_u32_e32 v129, s21, v126
	global_store_dword v129, v172, s[96:97]
	s_lshl_b32 s21, s56, 5
	s_add_u32 s21, s21, 0x314400f0
	v_add_u32_e32 v129, s21, v126
	global_store_dword v129, v173, s[96:97]
	s_mov_b64 exec, s[2:3]
	v_readlane_b32 s44, v244, 46
	v_readlane_b32 s45, v244, 47
	v_readlane_b32 s86, v244, 35
	v_readlane_b32 s87, v244, 36
	v_readlane_b32 s48, v244, 34
	v_readlane_b32 s50, v244, 33
	v_readlane_b32 s90, v244, 37
	v_readlane_b32 s91, v244, 38
	v_readlane_b32 s92, v244, 39
	v_readlane_b32 s93, v244, 40
	v_readlane_b32 s73, v244, 41
	s_movk_i32 s51, 0x3ff
	s_mov_b32 s67, 0x1000000
	s_mov_b64 s[0:1], exec
	s_branch .LBB0_333
